# GEMM K-loops: the barrier ending a half's MFMA block issued one MFMA before the block's end (it orders LDS slot reuse only), so the other half's MFMAs are released while the last one still runs
# speedup vs baseline: 1.0051x; 1.0043x over previous
; #define PG8_STAGE(bufoff, gbase, voff) do { _Pragma("unroll") for (int _i = 0; _i < 2; ++_i) \
;         __builtin_amdgcn_global_load_lds((const unsigned*)((const char*)(gbase) + (voff)[_i]), (PG8_LAS unsigned*)(lds + (bufoff) + ldsw + _i * 8192), 16, 0, 0); } while (0)
; #define PG8_LDA(dst, b, h) do { _Pragma("unroll") for (int m = 0; m < 4; ++m) _Pragma("unroll") for (int k = 0; k < 2; ++k) dst[m][k] = *(const PG8_LAS bf16x8*)(lds + PG8_SA(b, h) + aoff + m * 2048 + k * 1024); } while (0)
; #define PG8_LDB(dst, b, h) do { _Pragma("unroll") for (int n = 0; n < 2; ++n) _Pragma("unroll") for (int k = 0; k < 2; ++k) dst[n][k] = *(const PG8_LAS bf16x8*)(lds + PG8_SB(b, h) + boff + n * 2048 + k * 1024); } while (0)
; #define PG8_MMA(ai, bj, At, Bt) do { __builtin_amdgcn_s_setprio(1); _Pragma("unroll") for (int m = 0; m < 4; ++m) _Pragma("unroll") for (int n = 0; n < 2; ++n) _Pragma("unroll") for (int k = 0; k < 2; ++k) \
;         acc[ai][bj][m][n] = __builtin_amdgcn_mfma_f32_16x16x32_bf16(Bt[n][k], At[m][k], acc[ai][bj][m][n], 0, 0, 0); __builtin_amdgcn_s_setprio(0); } while (0)
; #define PG8_WAIT_V(n) asm volatile("s_waitcnt vmcnt(" #n ")" ::: "memory")
; #define PG8_WAIT_L(n) asm volatile("s_waitcnt lgkmcnt(" #n ")" ::: "memory")
; #define PG8_BAR __builtin_amdgcn_s_barrier()
; #define PG8_SCHED __builtin_amdgcn_sched_barrier(0)
; template <class Epi, class Sched, bool ALIGN_EPI = false, bool SP2 = false>
; __device__ __forceinline__ void gemm_phase(PG8_LAS unsigned char* lds, const Gemm g, const Sched& S, const Epi& E) {
;     ...
;             PG8_LDB(B0, 0, 0); PG8_LDB(B1, 0, 1); PG8_SCHED; PG8_LDA(At, 0, 0); PG8_STAGE(PG8_SA(1, 1), a1 + hstep, voffA);
;             PG8_WAIT_V(8); PG8_WAIT_L(0); PG8_BAR; PG8_MMA(0, 0, At, B0); PG8_MMA(0, 1, At, B1); PG8_BAR; PG8_SCHED;
;             PG8_LDA(At, 0, 1); PG8_STAGE(PG8_SB(0, 0), b2, voffB); PG8_STAGE(PG8_SB(0, 1), b2 + hstep, voffB); PG8_STAGE(PG8_SA(0, 0), a2, voffA);
.LBB0_121:
	s_add_u32 s46, s44, 0xfffc0080
	s_addc_u32 s47, s45, -1
	s_add_i32 s64, 0, 0x10000
	s_cmp_eq_u32 s63, 12
	s_cselect_b32 s49, s41, s47
	s_cselect_b32 s48, s40, s46
	v_add_u32_e32 v146, s64, v149
	s_cselect_b32 s47, s37, s62
	s_cselect_b32 s46, s39, s61
	s_add_i32 s67, 0, 0x14000
	ds_read_b128 v[152:155], v146
	ds_read_b128 v[156:159], v146 offset:1024
	ds_read_b128 v[160:163], v146 offset:2048
	ds_read_b128 v[174:177], v146 offset:3072
	v_add_u32_e32 v146, s67, v149
	ds_read_b128 v[178:181], v146
	ds_read_b128 v[182:185], v146 offset:1024
	ds_read_b128 v[186:189], v146 offset:2048
	ds_read_b128 v[190:193], v146 offset:3072
	v_lshl_add_u64 v[146:147], s[44:45], 0, v[142:143]
	s_add_i32 m0, s52, 0xc000
	ds_read_b128 v[194:197], v151
	ds_read_b128 v[198:201], v151 offset:1024
	ds_read_b128 v[202:205], v151 offset:2048
	ds_read_b128 v[206:209], v151 offset:3072
	ds_read_b128 v[210:213], v151 offset:4096
	ds_read_b128 v[214:217], v151 offset:5120
	ds_read_b128 v[218:221], v151 offset:6144
	ds_read_b128 v[222:225], v151 offset:7168
	global_load_lds_dwordx4 v[146:147], off
	v_lshl_add_u64 v[146:147], s[44:45], 0, v[144:145]
	s_add_i32 m0, s52, 0xe000
	s_nop 0
	global_load_lds_dwordx4 v[146:147], off
	s_waitcnt vmcnt(8)
	s_waitcnt lgkmcnt(0)
	s_barrier
	s_setprio 1
	s_waitcnt lgkmcnt(0)
	v_mfma_f32_16x16x32_bf16 v[126:129], v[152:155], v[194:197], v[126:129]
	v_mfma_f32_16x16x32_bf16 v[122:125], v[160:163], v[194:197], v[122:125]
	v_mfma_f32_16x16x32_bf16 v[118:121], v[152:155], v[202:205], v[118:121]
	v_mfma_f32_16x16x32_bf16 v[110:113], v[160:163], v[202:205], v[110:113]
	v_mfma_f32_16x16x32_bf16 v[102:105], v[152:155], v[210:213], v[102:105]
	v_mfma_f32_16x16x32_bf16 v[94:97], v[160:163], v[210:213], v[94:97]
	v_mfma_f32_16x16x32_bf16 v[86:89], v[152:155], v[218:221], v[86:89]
	v_mfma_f32_16x16x32_bf16 v[78:81], v[160:163], v[218:221], v[78:81]
	v_mfma_f32_16x16x32_bf16 v[126:129], v[156:159], v[198:201], v[126:129]
	v_mfma_f32_16x16x32_bf16 v[122:125], v[174:177], v[198:201], v[122:125]
	v_mfma_f32_16x16x32_bf16 v[118:121], v[156:159], v[206:209], v[118:121]
	v_mfma_f32_16x16x32_bf16 v[110:113], v[174:177], v[206:209], v[110:113]
	v_mfma_f32_16x16x32_bf16 v[102:105], v[156:159], v[214:217], v[102:105]
	v_mfma_f32_16x16x32_bf16 v[94:97], v[174:177], v[214:217], v[94:97]
	v_mfma_f32_16x16x32_bf16 v[86:89], v[156:159], v[222:225], v[86:89]
	v_mfma_f32_16x16x32_bf16 v[78:81], v[174:177], v[222:225], v[78:81]
	s_setprio 0
	s_setprio 1
	v_mfma_f32_16x16x32_bf16 v[114:117], v[178:181], v[194:197], v[114:117]
	v_mfma_f32_16x16x32_bf16 v[106:109], v[186:189], v[194:197], v[106:109]
	v_mfma_f32_16x16x32_bf16 v[98:101], v[178:181], v[202:205], v[98:101]
	v_mfma_f32_16x16x32_bf16 v[90:93], v[186:189], v[202:205], v[90:93]
	v_mfma_f32_16x16x32_bf16 v[82:85], v[178:181], v[210:213], v[82:85]
	v_mfma_f32_16x16x32_bf16 v[74:77], v[186:189], v[210:213], v[74:77]
	v_mfma_f32_16x16x32_bf16 v[70:73], v[178:181], v[218:221], v[70:73]
	v_mfma_f32_16x16x32_bf16 v[66:69], v[186:189], v[218:221], v[66:69]
	v_mfma_f32_16x16x32_bf16 v[114:117], v[182:185], v[198:201], v[114:117]
	v_mfma_f32_16x16x32_bf16 v[106:109], v[190:193], v[198:201], v[106:109]
	v_mfma_f32_16x16x32_bf16 v[98:101], v[182:185], v[206:209], v[98:101]
	v_mfma_f32_16x16x32_bf16 v[90:93], v[190:193], v[206:209], v[90:93]
	v_mfma_f32_16x16x32_bf16 v[82:85], v[182:185], v[214:217], v[82:85]
	v_mfma_f32_16x16x32_bf16 v[74:77], v[190:193], v[214:217], v[74:77]
	v_mfma_f32_16x16x32_bf16 v[70:73], v[182:185], v[222:225], v[70:73]
	s_barrier
	v_mfma_f32_16x16x32_bf16 v[66:69], v[190:193], v[222:225], v[66:69]
	s_setprio 0
	s_add_i32 s64, s64, s34
	v_lshl_add_u64 v[146:147], s[46:47], 0, v[130:131]
	s_mov_b32 m0, s64
	ds_read_b128 v[194:197], v151 offset:16384
	ds_read_b128 v[198:201], v151 offset:17408
	ds_read_b128 v[202:205], v151 offset:18432
	ds_read_b128 v[206:209], v151 offset:19456
	ds_read_b128 v[210:213], v151 offset:20480
	ds_read_b128 v[214:217], v151 offset:21504
	ds_read_b128 v[218:221], v151 offset:22528
	ds_read_b128 v[222:225], v151 offset:23552
	global_load_lds_dwordx4 v[146:147], off
	s_add_i32 m0, s64, 0x2000
	s_add_u32 s64, s46, 0x40000
	v_lshl_add_u64 v[226:227], s[46:47], 0, v[136:137]
	s_addc_u32 s65, s47, 0
	s_add_i32 s67, s67, s34
	global_load_lds_dwordx4 v[226:227], off
	v_lshl_add_u64 v[228:229], s[64:65], 0, v[130:131]
	s_mov_b32 m0, s67
	v_lshl_add_u64 v[230:231], s[48:49], 0, v[138:139]
	global_load_lds_dwordx4 v[228:229], off
	v_lshl_add_u64 v[228:229], s[64:65], 0, v[136:137]
	s_add_i32 m0, s67, 0x2000
	s_nop 0
	global_load_lds_dwordx4 v[228:229], off
	v_lshl_add_u64 v[228:229], s[48:49], 0, v[140:141]
	s_mov_b32 m0, s52
	s_nop 0
	global_load_lds_dwordx4 v[228:229], off
	s_mov_b32 m0, s53
	s_nop 0
	global_load_lds_dwordx4 v[230:231], off
	s_waitcnt vmcnt(8)
	s_waitcnt lgkmcnt(0)
	s_barrier
; #define PG8_STAGE(bufoff, gbase, voff) do { _Pragma("unroll") for (int _i = 0; _i < 2; ++_i) \
;         __builtin_amdgcn_global_load_lds((const unsigned*)((const char*)(gbase) + (voff)[_i]), (PG8_LAS unsigned*)(lds + (bufoff) + ldsw + _i * 8192), 16, 0, 0); } while (0)
; #define PG8_LDA(dst, b, h) do { _Pragma("unroll") for (int m = 0; m < 4; ++m) _Pragma("unroll") for (int k = 0; k < 2; ++k) dst[m][k] = *(const PG8_LAS bf16x8*)(lds + PG8_SA(b, h) + aoff + m * 2048 + k * 1024); } while (0)
; #define PG8_LDB(dst, b, h) do { _Pragma("unroll") for (int n = 0; n < 2; ++n) _Pragma("unroll") for (int k = 0; k < 2; ++k) dst[n][k] = *(const PG8_LAS bf16x8*)(lds + PG8_SB(b, h) + boff + n * 2048 + k * 1024); } while (0)
; #define PG8_MMA(ai, bj, At, Bt) do { __builtin_amdgcn_s_setprio(1); _Pragma("unroll") for (int m = 0; m < 4; ++m) _Pragma("unroll") for (int n = 0; n < 2; ++n) _Pragma("unroll") for (int k = 0; k < 2; ++k) \
;         acc[ai][bj][m][n] = __builtin_amdgcn_mfma_f32_16x16x32_bf16(Bt[n][k], At[m][k], acc[ai][bj][m][n], 0, 0, 0); __builtin_amdgcn_s_setprio(0); } while (0)
; #define PG8_WAIT_V(n) asm volatile("s_waitcnt vmcnt(" #n ")" ::: "memory")
; #define PG8_WAIT_L(n) asm volatile("s_waitcnt lgkmcnt(" #n ")" ::: "memory")
; #define PG8_BAR __builtin_amdgcn_s_barrier()
; #define PG8_SCHED __builtin_amdgcn_sched_barrier(0)
; template <class Epi, class Sched, bool ALIGN_EPI = false, bool SP2 = false>
; __device__ __forceinline__ void gemm_phase(PG8_LAS unsigned char* lds, const Gemm g, const Sched& S, const Epi& E) {
;     ...
;             PG8_WAIT_V(8); PG8_WAIT_L(0); PG8_BAR; PG8_MMA(1, 0, At, B0); PG8_MMA(1, 1, At, B1); PG8_BAR; PG8_SCHED;
;             PG8_LDB(B0, 1, 0); PG8_LDB(B1, 1, 1); PG8_SCHED; PG8_LDA(At, 1, 0); PG8_STAGE(PG8_SA(0, 1), a2 + hstep, voffA);
;             PG8_WAIT_V(8); PG8_WAIT_L(0); PG8_BAR; PG8_MMA(0, 0, At, B0); PG8_MMA(0, 1, At, B1); PG8_BAR; PG8_SCHED;
	s_setprio 1
	s_waitcnt lgkmcnt(0)
	v_mfma_f32_16x16x32_bf16 v[62:65], v[152:155], v[194:197], v[62:65]
	v_mfma_f32_16x16x32_bf16 v[58:61], v[160:163], v[194:197], v[58:61]
	v_mfma_f32_16x16x32_bf16 v[54:57], v[152:155], v[202:205], v[54:57]
	v_mfma_f32_16x16x32_bf16 v[46:49], v[160:163], v[202:205], v[46:49]
	v_mfma_f32_16x16x32_bf16 v[38:41], v[152:155], v[210:213], v[38:41]
	v_mfma_f32_16x16x32_bf16 v[30:33], v[160:163], v[210:213], v[30:33]
	v_mfma_f32_16x16x32_bf16 v[22:25], v[152:155], v[218:221], v[22:25]
	v_mfma_f32_16x16x32_bf16 v[14:17], v[160:163], v[218:221], v[14:17]
	v_mfma_f32_16x16x32_bf16 v[62:65], v[156:159], v[198:201], v[62:65]
	v_mfma_f32_16x16x32_bf16 v[58:61], v[174:177], v[198:201], v[58:61]
	v_mfma_f32_16x16x32_bf16 v[54:57], v[156:159], v[206:209], v[54:57]
	v_mfma_f32_16x16x32_bf16 v[46:49], v[174:177], v[206:209], v[46:49]
	v_mfma_f32_16x16x32_bf16 v[38:41], v[156:159], v[214:217], v[38:41]
	v_mfma_f32_16x16x32_bf16 v[30:33], v[174:177], v[214:217], v[30:33]
	v_mfma_f32_16x16x32_bf16 v[22:25], v[156:159], v[222:225], v[22:25]
	v_mfma_f32_16x16x32_bf16 v[14:17], v[174:177], v[222:225], v[14:17]
	s_setprio 0
	s_setprio 1
	v_mfma_f32_16x16x32_bf16 v[50:53], v[178:181], v[194:197], v[50:53]
	v_mfma_f32_16x16x32_bf16 v[42:45], v[186:189], v[194:197], v[42:45]
	v_mfma_f32_16x16x32_bf16 v[34:37], v[178:181], v[202:205], v[34:37]
	v_mfma_f32_16x16x32_bf16 v[26:29], v[186:189], v[202:205], v[26:29]
	v_mfma_f32_16x16x32_bf16 v[18:21], v[178:181], v[210:213], v[18:21]
	v_mfma_f32_16x16x32_bf16 v[10:13], v[186:189], v[210:213], v[10:13]
	v_mfma_f32_16x16x32_bf16 v[6:9], v[178:181], v[218:221], v[6:9]
	v_mfma_f32_16x16x32_bf16 v[2:5], v[186:189], v[218:221], v[2:5]
	v_mfma_f32_16x16x32_bf16 v[50:53], v[182:185], v[198:201], v[50:53]
	v_mfma_f32_16x16x32_bf16 v[42:45], v[190:193], v[198:201], v[42:45]
	v_mfma_f32_16x16x32_bf16 v[34:37], v[182:185], v[206:209], v[34:37]
	v_mfma_f32_16x16x32_bf16 v[26:29], v[190:193], v[206:209], v[26:29]
	v_mfma_f32_16x16x32_bf16 v[18:21], v[182:185], v[214:217], v[18:21]
	v_mfma_f32_16x16x32_bf16 v[10:13], v[190:193], v[214:217], v[10:13]
	v_mfma_f32_16x16x32_bf16 v[6:9], v[182:185], v[222:225], v[6:9]
	s_barrier
	v_mfma_f32_16x16x32_bf16 v[2:5], v[190:193], v[222:225], v[2:5]
	s_setprio 0
	s_add_i32 s64, 0, 0x18000
	v_add_u32_e32 v173, s64, v149
	s_add_i32 s65, 0, 0x1c000
	ds_read_b128 v[152:155], v173
	ds_read_b128 v[156:159], v173 offset:1024
	ds_read_b128 v[160:163], v173 offset:2048
	ds_read_b128 v[174:177], v173 offset:3072
	v_add_u32_e32 v173, s65, v149
	ds_read_b128 v[178:181], v173
	ds_read_b128 v[182:185], v173 offset:1024
	ds_read_b128 v[186:189], v173 offset:2048
	ds_read_b128 v[190:193], v173 offset:3072
	s_add_u32 s48, s48, 0x40000
	s_addc_u32 s49, s49, 0
	s_mov_b32 m0, s54
	v_lshl_add_u64 v[232:233], s[48:49], 0, v[140:141]
	ds_read_b128 v[194:197], v151 offset:32768
	ds_read_b128 v[198:201], v151 offset:33792
	ds_read_b128 v[202:205], v151 offset:34816
	ds_read_b128 v[206:209], v151 offset:35840
	ds_read_b128 v[210:213], v151 offset:36864
	ds_read_b128 v[214:217], v151 offset:37888
	ds_read_b128 v[218:221], v151 offset:38912
	ds_read_b128 v[222:225], v151 offset:39936
	global_load_lds_dwordx4 v[232:233], off
	v_lshl_add_u64 v[232:233], s[48:49], 0, v[138:139]
	s_mov_b32 m0, s55
	s_nop 0
	global_load_lds_dwordx4 v[232:233], off
	s_waitcnt vmcnt(8)
	s_waitcnt lgkmcnt(0)
	s_barrier
	s_setprio 1
	s_waitcnt lgkmcnt(0)
	v_mfma_f32_16x16x32_bf16 v[126:129], v[152:155], v[194:197], v[126:129]
	v_mfma_f32_16x16x32_bf16 v[122:125], v[160:163], v[194:197], v[122:125]
	v_mfma_f32_16x16x32_bf16 v[118:121], v[152:155], v[202:205], v[118:121]
	v_mfma_f32_16x16x32_bf16 v[110:113], v[160:163], v[202:205], v[110:113]
	v_mfma_f32_16x16x32_bf16 v[102:105], v[152:155], v[210:213], v[102:105]
	v_mfma_f32_16x16x32_bf16 v[94:97], v[160:163], v[210:213], v[94:97]
	v_mfma_f32_16x16x32_bf16 v[86:89], v[152:155], v[218:221], v[86:89]
	v_mfma_f32_16x16x32_bf16 v[78:81], v[160:163], v[218:221], v[78:81]
	v_mfma_f32_16x16x32_bf16 v[126:129], v[156:159], v[198:201], v[126:129]
	v_mfma_f32_16x16x32_bf16 v[122:125], v[174:177], v[198:201], v[122:125]
	v_mfma_f32_16x16x32_bf16 v[118:121], v[156:159], v[206:209], v[118:121]
	v_mfma_f32_16x16x32_bf16 v[110:113], v[174:177], v[206:209], v[110:113]
	v_mfma_f32_16x16x32_bf16 v[102:105], v[156:159], v[214:217], v[102:105]
	v_mfma_f32_16x16x32_bf16 v[94:97], v[174:177], v[214:217], v[94:97]
	v_mfma_f32_16x16x32_bf16 v[86:89], v[156:159], v[222:225], v[86:89]
	v_mfma_f32_16x16x32_bf16 v[78:81], v[174:177], v[222:225], v[78:81]
	s_setprio 0
	s_setprio 1
	v_mfma_f32_16x16x32_bf16 v[114:117], v[178:181], v[194:197], v[114:117]
	v_mfma_f32_16x16x32_bf16 v[106:109], v[186:189], v[194:197], v[106:109]
	v_mfma_f32_16x16x32_bf16 v[98:101], v[178:181], v[202:205], v[98:101]
	v_mfma_f32_16x16x32_bf16 v[90:93], v[186:189], v[202:205], v[90:93]
	v_mfma_f32_16x16x32_bf16 v[82:85], v[178:181], v[210:213], v[82:85]
	v_mfma_f32_16x16x32_bf16 v[74:77], v[186:189], v[210:213], v[74:77]
	v_mfma_f32_16x16x32_bf16 v[70:73], v[178:181], v[218:221], v[70:73]
	v_mfma_f32_16x16x32_bf16 v[66:69], v[186:189], v[218:221], v[66:69]
	v_mfma_f32_16x16x32_bf16 v[114:117], v[182:185], v[198:201], v[114:117]
	v_mfma_f32_16x16x32_bf16 v[106:109], v[190:193], v[198:201], v[106:109]
	v_mfma_f32_16x16x32_bf16 v[98:101], v[182:185], v[206:209], v[98:101]
	v_mfma_f32_16x16x32_bf16 v[90:93], v[190:193], v[206:209], v[90:93]
	v_mfma_f32_16x16x32_bf16 v[82:85], v[182:185], v[214:217], v[82:85]
	v_mfma_f32_16x16x32_bf16 v[74:77], v[190:193], v[214:217], v[74:77]
	v_mfma_f32_16x16x32_bf16 v[70:73], v[182:185], v[222:225], v[70:73]
	s_barrier
; #define PG8_STAGE(bufoff, gbase, voff) do { _Pragma("unroll") for (int _i = 0; _i < 2; ++_i) \
;         __builtin_amdgcn_global_load_lds((const unsigned*)((const char*)(gbase) + (voff)[_i]), (PG8_LAS unsigned*)(lds + (bufoff) + ldsw + _i * 8192), 16, 0, 0); } while (0)
; #define PG8_LDA(dst, b, h) do { _Pragma("unroll") for (int m = 0; m < 4; ++m) _Pragma("unroll") for (int k = 0; k < 2; ++k) dst[m][k] = *(const PG8_LAS bf16x8*)(lds + PG8_SA(b, h) + aoff + m * 2048 + k * 1024); } while (0)
; #define PG8_MMA(ai, bj, At, Bt) do { __builtin_amdgcn_s_setprio(1); _Pragma("unroll") for (int m = 0; m < 4; ++m) _Pragma("unroll") for (int n = 0; n < 2; ++n) _Pragma("unroll") for (int k = 0; k < 2; ++k) \
;         acc[ai][bj][m][n] = __builtin_amdgcn_mfma_f32_16x16x32_bf16(Bt[n][k], At[m][k], acc[ai][bj][m][n], 0, 0, 0); __builtin_amdgcn_s_setprio(0); } while (0)
; #define PG8_WAIT_V(n) asm volatile("s_waitcnt vmcnt(" #n ")" ::: "memory")
; #define PG8_WAIT_L(n) asm volatile("s_waitcnt lgkmcnt(" #n ")" ::: "memory")
; #define PG8_BAR __builtin_amdgcn_s_barrier()
; #define PG8_SCHED __builtin_amdgcn_sched_barrier(0)
; template <class Epi, class Sched, bool ALIGN_EPI = false, bool SP2 = false>
; __device__ __forceinline__ void gemm_phase(PG8_LAS unsigned char* lds, const Gemm g, const Sched& S, const Epi& E) {
;     ...
;             PG8_LDA(At, 1, 1); PG8_STAGE(PG8_SB(1, 0), b3, voffB); PG8_STAGE(PG8_SB(1, 1), b3 + hstep, voffB); PG8_STAGE(PG8_SA(1, 0), a3, voffA);
;             PG8_WAIT_V(8); PG8_WAIT_L(0); PG8_BAR; PG8_MMA(1, 0, At, B0); PG8_MMA(1, 1, At, B1); PG8_BAR; PG8_SCHED;
;     ...
;         if constexpr (ALIGN_EPI) { if (wr == 0) PG8_BAR; }
	v_mfma_f32_16x16x32_bf16 v[66:69], v[190:193], v[222:225], v[66:69]
	s_setprio 0
	s_add_i32 s48, s64, s34
	v_lshl_add_u64 v[146:147], v[146:147], 0, s[96:97]
	s_mov_b32 m0, s48
	ds_read_b128 v[194:197], v151 offset:49152
	ds_read_b128 v[198:201], v151 offset:50176
	ds_read_b128 v[202:205], v151 offset:51200
	ds_read_b128 v[206:209], v151 offset:52224
	ds_read_b128 v[210:213], v151 offset:53248
	ds_read_b128 v[214:217], v151 offset:54272
	ds_read_b128 v[218:221], v151 offset:55296
	ds_read_b128 v[222:225], v151 offset:56320
	global_load_lds_dwordx4 v[146:147], off
	s_add_i32 m0, s48, 0x2000
	s_add_u32 s46, s46, 0x40080
	v_lshl_add_u64 v[146:147], v[226:227], 0, s[96:97]
	s_addc_u32 s47, s47, 0
	s_add_i32 s48, s65, s34
	global_load_lds_dwordx4 v[146:147], off
	v_lshl_add_u64 v[146:147], s[46:47], 0, v[130:131]
	s_mov_b32 m0, s48
	s_nop 0
	global_load_lds_dwordx4 v[146:147], off
	v_lshl_add_u64 v[146:147], s[46:47], 0, v[136:137]
	s_add_i32 m0, s48, 0x2000
	s_nop 0
	global_load_lds_dwordx4 v[146:147], off
	v_lshl_add_u64 v[146:147], v[228:229], 0, s[96:97]
	s_mov_b32 m0, s56
	s_nop 0
	global_load_lds_dwordx4 v[146:147], off
	v_lshl_add_u64 v[146:147], v[230:231], 0, s[96:97]
	s_mov_b32 m0, s57
	s_nop 0
	global_load_lds_dwordx4 v[146:147], off
	s_waitcnt vmcnt(8)
	s_waitcnt lgkmcnt(0)
	s_barrier
	s_setprio 1
	s_waitcnt lgkmcnt(0)
	v_mfma_f32_16x16x32_bf16 v[62:65], v[152:155], v[194:197], v[62:65]
	v_mfma_f32_16x16x32_bf16 v[58:61], v[160:163], v[194:197], v[58:61]
	v_mfma_f32_16x16x32_bf16 v[54:57], v[152:155], v[202:205], v[54:57]
	v_mfma_f32_16x16x32_bf16 v[46:49], v[160:163], v[202:205], v[46:49]
	v_mfma_f32_16x16x32_bf16 v[38:41], v[152:155], v[210:213], v[38:41]
	v_mfma_f32_16x16x32_bf16 v[30:33], v[160:163], v[210:213], v[30:33]
	v_mfma_f32_16x16x32_bf16 v[22:25], v[152:155], v[218:221], v[22:25]
	v_mfma_f32_16x16x32_bf16 v[14:17], v[160:163], v[218:221], v[14:17]
	v_mfma_f32_16x16x32_bf16 v[62:65], v[156:159], v[198:201], v[62:65]
	v_mfma_f32_16x16x32_bf16 v[58:61], v[174:177], v[198:201], v[58:61]
	v_mfma_f32_16x16x32_bf16 v[54:57], v[156:159], v[206:209], v[54:57]
	v_mfma_f32_16x16x32_bf16 v[46:49], v[174:177], v[206:209], v[46:49]
	v_mfma_f32_16x16x32_bf16 v[38:41], v[156:159], v[214:217], v[38:41]
	v_mfma_f32_16x16x32_bf16 v[30:33], v[174:177], v[214:217], v[30:33]
	v_mfma_f32_16x16x32_bf16 v[22:25], v[156:159], v[222:225], v[22:25]
	v_mfma_f32_16x16x32_bf16 v[14:17], v[174:177], v[222:225], v[14:17]
	s_setprio 0
	s_setprio 1
	v_mfma_f32_16x16x32_bf16 v[50:53], v[178:181], v[194:197], v[50:53]
	v_mfma_f32_16x16x32_bf16 v[42:45], v[186:189], v[194:197], v[42:45]
	v_mfma_f32_16x16x32_bf16 v[34:37], v[178:181], v[202:205], v[34:37]
	v_mfma_f32_16x16x32_bf16 v[26:29], v[186:189], v[202:205], v[26:29]
	v_mfma_f32_16x16x32_bf16 v[18:21], v[178:181], v[210:213], v[18:21]
	v_mfma_f32_16x16x32_bf16 v[10:13], v[186:189], v[210:213], v[10:13]
	v_mfma_f32_16x16x32_bf16 v[6:9], v[178:181], v[218:221], v[6:9]
	v_mfma_f32_16x16x32_bf16 v[2:5], v[186:189], v[218:221], v[2:5]
	v_mfma_f32_16x16x32_bf16 v[50:53], v[182:185], v[198:201], v[50:53]
	v_mfma_f32_16x16x32_bf16 v[42:45], v[190:193], v[198:201], v[42:45]
	v_mfma_f32_16x16x32_bf16 v[34:37], v[182:185], v[206:209], v[34:37]
	v_mfma_f32_16x16x32_bf16 v[26:29], v[190:193], v[206:209], v[26:29]
	v_mfma_f32_16x16x32_bf16 v[18:21], v[182:185], v[214:217], v[18:21]
	v_mfma_f32_16x16x32_bf16 v[10:13], v[190:193], v[214:217], v[10:13]
	v_mfma_f32_16x16x32_bf16 v[6:9], v[182:185], v[222:225], v[6:9]
	s_barrier
	v_mfma_f32_16x16x32_bf16 v[2:5], v[190:193], v[222:225], v[2:5]
	s_setprio 0
	s_add_i32 s63, s63, 2
	s_add_u32 s44, s44, 0x100
	s_addc_u32 s45, s45, 0
	s_add_u32 s61, s61, 0x100
	s_addc_u32 s62, s62, 0
	s_cmp_gt_u32 s63, 13
	s_cbranch_scc0 .LBB0_121
	s_and_b64 vcc, exec, s[6:7]
	s_cbranch_vccz .LBB0_124
	s_barrier

; #define PG8_STAGE(bufoff, gbase, voff) do { _Pragma("unroll") for (int _i = 0; _i < 2; ++_i) \
;         __builtin_amdgcn_global_load_lds((const unsigned*)((const char*)(gbase) + (voff)[_i]), (PG8_LAS unsigned*)(lds + (bufoff) + ldsw + _i * 8192), 16, 0, 0); } while (0)
; #define PG8_LDA(dst, b, h) do { _Pragma("unroll") for (int m = 0; m < 4; ++m) _Pragma("unroll") for (int k = 0; k < 2; ++k) dst[m][k] = *(const PG8_LAS bf16x8*)(lds + PG8_SA(b, h) + aoff + m * 2048 + k * 1024); } while (0)
; #define PG8_LDB(dst, b, h) do { _Pragma("unroll") for (int n = 0; n < 2; ++n) _Pragma("unroll") for (int k = 0; k < 2; ++k) dst[n][k] = *(const PG8_LAS bf16x8*)(lds + PG8_SB(b, h) + boff + n * 2048 + k * 1024); } while (0)
; #define PG8_MMA(ai, bj, At, Bt) do { __builtin_amdgcn_s_setprio(1); _Pragma("unroll") for (int m = 0; m < 4; ++m) _Pragma("unroll") for (int n = 0; n < 2; ++n) _Pragma("unroll") for (int k = 0; k < 2; ++k) \
;         acc[ai][bj][m][n] = __builtin_amdgcn_mfma_f32_16x16x32_bf16(Bt[n][k], At[m][k], acc[ai][bj][m][n], 0, 0, 0); __builtin_amdgcn_s_setprio(0); } while (0)
; #define PG8_WAIT_V(n) asm volatile("s_waitcnt vmcnt(" #n ")" ::: "memory")
; #define PG8_WAIT_L(n) asm volatile("s_waitcnt lgkmcnt(" #n ")" ::: "memory")
; #define PG8_BAR __builtin_amdgcn_s_barrier()
; #define PG8_SCHED __builtin_amdgcn_sched_barrier(0)
; template <class Epi, class Sched, bool ALIGN_EPI = false, bool SP2 = false>
; __device__ __forceinline__ void gemm_phase(PG8_LAS unsigned char* lds, const Gemm g, const Sched& S, const Epi& E) {
;     ...
;             PG8_LDB(B0, 0, 0); PG8_LDB(B1, 0, 1); PG8_SCHED; PG8_LDA(At, 0, 0); PG8_STAGE(PG8_SA(1, 1), a1 + hstep, voffA);
;             PG8_WAIT_V(8); PG8_WAIT_L(0); PG8_BAR; PG8_MMA(0, 0, At, B0); PG8_MMA(0, 1, At, B1); PG8_BAR; PG8_SCHED;
;             PG8_LDA(At, 0, 1); PG8_STAGE(PG8_SB(0, 0), b2, voffB); PG8_STAGE(PG8_SB(0, 1), b2 + hstep, voffB); PG8_STAGE(PG8_SA(0, 0), a2, voffA);
.LBB0_811:
	ds_read_b128 v[130:133], v159
	ds_read_b128 v[152:155], v159 offset:1024
	ds_read_b128 v[166:169], v159 offset:2048
	ds_read_b128 v[170:173], v159 offset:3072
	ds_read_b128 v[174:177], v160
	ds_read_b128 v[178:181], v160 offset:1024
	ds_read_b128 v[182:185], v160 offset:2048
	ds_read_b128 v[186:189], v160 offset:3072
	s_add_u32 s42, s4, 0xfffc0080
	s_addc_u32 s43, s5, -1
	s_cmp_eq_u32 s47, 12
	s_cselect_b32 s45, s35, s43
	s_cselect_b32 s44, s34, s42
	s_cselect_b32 s43, s6, s46
	s_cselect_b32 s42, s23, s25
	v_lshl_add_u64 v[162:163], s[4:5], 0, v[144:145]
	s_add_i32 m0, s39, 0xc000
	ds_read_b128 v[190:193], v161
	ds_read_b128 v[194:197], v161 offset:1024
	ds_read_b128 v[198:201], v161 offset:2048
	ds_read_b128 v[202:205], v161 offset:3072
	ds_read_b128 v[206:209], v161 offset:4096
	ds_read_b128 v[210:213], v161 offset:5120
	ds_read_b128 v[214:217], v161 offset:6144
	ds_read_b128 v[218:221], v161 offset:7168
	global_load_lds_dwordx4 v[162:163], off
	v_lshl_add_u64 v[162:163], s[4:5], 0, v[146:147]
	s_add_i32 m0, s39, 0xe000
	s_nop 0
	global_load_lds_dwordx4 v[162:163], off
	s_waitcnt vmcnt(8)
	s_waitcnt lgkmcnt(0)
	s_barrier
	s_setprio 1
	s_waitcnt lgkmcnt(0)
	v_mfma_f32_16x16x32_bf16 v[126:129], v[130:133], v[190:193], v[126:129]
	v_mfma_f32_16x16x32_bf16 v[122:125], v[166:169], v[190:193], v[122:125]
	v_mfma_f32_16x16x32_bf16 v[110:113], v[130:133], v[198:201], v[110:113]
	v_mfma_f32_16x16x32_bf16 v[106:109], v[166:169], v[198:201], v[106:109]
	v_mfma_f32_16x16x32_bf16 v[94:97], v[130:133], v[206:209], v[94:97]
	v_mfma_f32_16x16x32_bf16 v[90:93], v[166:169], v[206:209], v[90:93]
	v_mfma_f32_16x16x32_bf16 v[78:81], v[130:133], v[214:217], v[78:81]
	v_mfma_f32_16x16x32_bf16 v[74:77], v[166:169], v[214:217], v[74:77]
	v_mfma_f32_16x16x32_bf16 v[126:129], v[152:155], v[194:197], v[126:129]
	v_mfma_f32_16x16x32_bf16 v[122:125], v[170:173], v[194:197], v[122:125]
	v_mfma_f32_16x16x32_bf16 v[110:113], v[152:155], v[202:205], v[110:113]
	v_mfma_f32_16x16x32_bf16 v[106:109], v[170:173], v[202:205], v[106:109]
	v_mfma_f32_16x16x32_bf16 v[94:97], v[152:155], v[210:213], v[94:97]
	v_mfma_f32_16x16x32_bf16 v[90:93], v[170:173], v[210:213], v[90:93]
	v_mfma_f32_16x16x32_bf16 v[78:81], v[152:155], v[218:221], v[78:81]
	v_mfma_f32_16x16x32_bf16 v[74:77], v[170:173], v[218:221], v[74:77]
	s_setprio 0
	s_setprio 1
	v_mfma_f32_16x16x32_bf16 v[118:121], v[174:177], v[190:193], v[118:121]
	v_mfma_f32_16x16x32_bf16 v[114:117], v[182:185], v[190:193], v[114:117]
	v_mfma_f32_16x16x32_bf16 v[102:105], v[174:177], v[198:201], v[102:105]
	v_mfma_f32_16x16x32_bf16 v[98:101], v[182:185], v[198:201], v[98:101]
	v_mfma_f32_16x16x32_bf16 v[86:89], v[174:177], v[206:209], v[86:89]
	v_mfma_f32_16x16x32_bf16 v[82:85], v[182:185], v[206:209], v[82:85]
	v_mfma_f32_16x16x32_bf16 v[70:73], v[174:177], v[214:217], v[70:73]
	v_mfma_f32_16x16x32_bf16 v[66:69], v[182:185], v[214:217], v[66:69]
	v_mfma_f32_16x16x32_bf16 v[118:121], v[178:181], v[194:197], v[118:121]
	v_mfma_f32_16x16x32_bf16 v[114:117], v[186:189], v[194:197], v[114:117]
	v_mfma_f32_16x16x32_bf16 v[102:105], v[178:181], v[202:205], v[102:105]
	v_mfma_f32_16x16x32_bf16 v[98:101], v[186:189], v[202:205], v[98:101]
	v_mfma_f32_16x16x32_bf16 v[86:89], v[178:181], v[210:213], v[86:89]
	v_mfma_f32_16x16x32_bf16 v[82:85], v[186:189], v[210:213], v[82:85]
	v_mfma_f32_16x16x32_bf16 v[70:73], v[178:181], v[218:221], v[70:73]
	s_barrier
	v_mfma_f32_16x16x32_bf16 v[66:69], v[186:189], v[218:221], v[66:69]
	s_setprio 0
	s_add_i32 s61, s54, s33
	v_lshl_add_u64 v[162:163], s[42:43], 0, v[136:137]
	s_mov_b32 m0, s61
	ds_read_b128 v[190:193], v161 offset:16384
	ds_read_b128 v[194:197], v161 offset:17408
	ds_read_b128 v[198:201], v161 offset:18432
	ds_read_b128 v[202:205], v161 offset:19456
	ds_read_b128 v[206:209], v161 offset:20480
	ds_read_b128 v[210:213], v161 offset:21504
	ds_read_b128 v[214:217], v161 offset:22528
	ds_read_b128 v[218:221], v161 offset:23552
	global_load_lds_dwordx4 v[162:163], off
	s_add_i32 m0, s61, 0x2000
	s_add_u32 s62, s42, 0x40000
	v_lshl_add_u64 v[222:223], s[42:43], 0, v[140:141]
	s_addc_u32 s63, s43, 0
	s_add_i32 s61, s55, s33
	global_load_lds_dwordx4 v[222:223], off
	v_lshl_add_u64 v[224:225], s[62:63], 0, v[136:137]
	s_mov_b32 m0, s61
	v_lshl_add_u64 v[226:227], s[44:45], 0, v[138:139]
	global_load_lds_dwordx4 v[224:225], off
	v_lshl_add_u64 v[224:225], s[62:63], 0, v[140:141]
	s_add_i32 m0, s61, 0x2000
	s_nop 0
	global_load_lds_dwordx4 v[224:225], off
	v_lshl_add_u64 v[224:225], s[44:45], 0, v[134:135]
	s_mov_b32 m0, s39
	s_nop 0
	global_load_lds_dwordx4 v[224:225], off
	s_mov_b32 m0, s49
	s_nop 0
	global_load_lds_dwordx4 v[226:227], off
	s_waitcnt vmcnt(8)
	s_waitcnt lgkmcnt(0)
	s_barrier
; #define PG8_STAGE(bufoff, gbase, voff) do { _Pragma("unroll") for (int _i = 0; _i < 2; ++_i) \
;         __builtin_amdgcn_global_load_lds((const unsigned*)((const char*)(gbase) + (voff)[_i]), (PG8_LAS unsigned*)(lds + (bufoff) + ldsw + _i * 8192), 16, 0, 0); } while (0)
; #define PG8_LDA(dst, b, h) do { _Pragma("unroll") for (int m = 0; m < 4; ++m) _Pragma("unroll") for (int k = 0; k < 2; ++k) dst[m][k] = *(const PG8_LAS bf16x8*)(lds + PG8_SA(b, h) + aoff + m * 2048 + k * 1024); } while (0)
; #define PG8_LDB(dst, b, h) do { _Pragma("unroll") for (int n = 0; n < 2; ++n) _Pragma("unroll") for (int k = 0; k < 2; ++k) dst[n][k] = *(const PG8_LAS bf16x8*)(lds + PG8_SB(b, h) + boff + n * 2048 + k * 1024); } while (0)
; #define PG8_MMA(ai, bj, At, Bt) do { __builtin_amdgcn_s_setprio(1); _Pragma("unroll") for (int m = 0; m < 4; ++m) _Pragma("unroll") for (int n = 0; n < 2; ++n) _Pragma("unroll") for (int k = 0; k < 2; ++k) \
;         acc[ai][bj][m][n] = __builtin_amdgcn_mfma_f32_16x16x32_bf16(Bt[n][k], At[m][k], acc[ai][bj][m][n], 0, 0, 0); __builtin_amdgcn_s_setprio(0); } while (0)
; #define PG8_WAIT_V(n) asm volatile("s_waitcnt vmcnt(" #n ")" ::: "memory")
; #define PG8_WAIT_L(n) asm volatile("s_waitcnt lgkmcnt(" #n ")" ::: "memory")
; #define PG8_BAR __builtin_amdgcn_s_barrier()
; #define PG8_SCHED __builtin_amdgcn_sched_barrier(0)
; template <class Epi, class Sched, bool ALIGN_EPI = false, bool SP2 = false>
; __device__ __forceinline__ void gemm_phase(PG8_LAS unsigned char* lds, const Gemm g, const Sched& S, const Epi& E) {
;     ...
;             PG8_WAIT_V(8); PG8_WAIT_L(0); PG8_BAR; PG8_MMA(1, 0, At, B0); PG8_MMA(1, 1, At, B1); PG8_BAR; PG8_SCHED;
;             PG8_LDB(B0, 1, 0); PG8_LDB(B1, 1, 1); PG8_SCHED; PG8_LDA(At, 1, 0); PG8_STAGE(PG8_SA(0, 1), a2 + hstep, voffA);
;             PG8_WAIT_V(8); PG8_WAIT_L(0); PG8_BAR; PG8_MMA(0, 0, At, B0); PG8_MMA(0, 1, At, B1); PG8_BAR; PG8_SCHED;
	s_setprio 1
	s_waitcnt lgkmcnt(0)
	v_mfma_f32_16x16x32_bf16 v[62:65], v[130:133], v[190:193], v[62:65]
	v_mfma_f32_16x16x32_bf16 v[58:61], v[166:169], v[190:193], v[58:61]
	v_mfma_f32_16x16x32_bf16 v[46:49], v[130:133], v[198:201], v[46:49]
	v_mfma_f32_16x16x32_bf16 v[42:45], v[166:169], v[198:201], v[42:45]
	v_mfma_f32_16x16x32_bf16 v[30:33], v[130:133], v[206:209], v[30:33]
	v_mfma_f32_16x16x32_bf16 v[26:29], v[166:169], v[206:209], v[26:29]
	v_mfma_f32_16x16x32_bf16 v[14:17], v[130:133], v[214:217], v[14:17]
	v_mfma_f32_16x16x32_bf16 v[10:13], v[166:169], v[214:217], v[10:13]
	v_mfma_f32_16x16x32_bf16 v[62:65], v[152:155], v[194:197], v[62:65]
	v_mfma_f32_16x16x32_bf16 v[58:61], v[170:173], v[194:197], v[58:61]
	v_mfma_f32_16x16x32_bf16 v[46:49], v[152:155], v[202:205], v[46:49]
	v_mfma_f32_16x16x32_bf16 v[42:45], v[170:173], v[202:205], v[42:45]
	v_mfma_f32_16x16x32_bf16 v[30:33], v[152:155], v[210:213], v[30:33]
	v_mfma_f32_16x16x32_bf16 v[26:29], v[170:173], v[210:213], v[26:29]
	v_mfma_f32_16x16x32_bf16 v[14:17], v[152:155], v[218:221], v[14:17]
	v_mfma_f32_16x16x32_bf16 v[10:13], v[170:173], v[218:221], v[10:13]
	s_setprio 0
	s_setprio 1
	v_mfma_f32_16x16x32_bf16 v[54:57], v[174:177], v[190:193], v[54:57]
	v_mfma_f32_16x16x32_bf16 v[50:53], v[182:185], v[190:193], v[50:53]
	v_mfma_f32_16x16x32_bf16 v[38:41], v[174:177], v[198:201], v[38:41]
	v_mfma_f32_16x16x32_bf16 v[34:37], v[182:185], v[198:201], v[34:37]
	v_mfma_f32_16x16x32_bf16 v[22:25], v[174:177], v[206:209], v[22:25]
	v_mfma_f32_16x16x32_bf16 v[18:21], v[182:185], v[206:209], v[18:21]
	v_mfma_f32_16x16x32_bf16 v[6:9], v[174:177], v[214:217], v[6:9]
	v_mfma_f32_16x16x32_bf16 v[2:5], v[182:185], v[214:217], v[2:5]
	v_mfma_f32_16x16x32_bf16 v[54:57], v[178:181], v[194:197], v[54:57]
	v_mfma_f32_16x16x32_bf16 v[50:53], v[186:189], v[194:197], v[50:53]
	v_mfma_f32_16x16x32_bf16 v[38:41], v[178:181], v[202:205], v[38:41]
	v_mfma_f32_16x16x32_bf16 v[34:37], v[186:189], v[202:205], v[34:37]
	v_mfma_f32_16x16x32_bf16 v[22:25], v[178:181], v[210:213], v[22:25]
	v_mfma_f32_16x16x32_bf16 v[18:21], v[186:189], v[210:213], v[18:21]
	v_mfma_f32_16x16x32_bf16 v[6:9], v[178:181], v[218:221], v[6:9]
	s_barrier
	v_mfma_f32_16x16x32_bf16 v[2:5], v[186:189], v[218:221], v[2:5]
	s_setprio 0
	s_add_i32 s61, 0, 0x18000
	v_add_u32_e32 v142, s61, v157
	s_add_i32 s62, 0, 0x1c000
	ds_read_b128 v[130:133], v142
	ds_read_b128 v[152:155], v142 offset:1024
	ds_read_b128 v[166:169], v142 offset:2048
	ds_read_b128 v[170:173], v142 offset:3072
	v_add_u32_e32 v142, s62, v157
	ds_read_b128 v[174:177], v142
	ds_read_b128 v[178:181], v142 offset:1024
	ds_read_b128 v[182:185], v142 offset:2048
	ds_read_b128 v[186:189], v142 offset:3072
	s_add_u32 s44, s44, 0x40000
	s_addc_u32 s45, s45, 0
	s_mov_b32 m0, s50
	v_lshl_add_u64 v[228:229], s[44:45], 0, v[134:135]
	ds_read_b128 v[190:193], v161 offset:32768
	ds_read_b128 v[194:197], v161 offset:33792
	ds_read_b128 v[198:201], v161 offset:34816
	ds_read_b128 v[202:205], v161 offset:35840
	ds_read_b128 v[206:209], v161 offset:36864
	ds_read_b128 v[210:213], v161 offset:37888
	ds_read_b128 v[214:217], v161 offset:38912
	ds_read_b128 v[218:221], v161 offset:39936
	global_load_lds_dwordx4 v[228:229], off
	v_lshl_add_u64 v[228:229], s[44:45], 0, v[138:139]
	s_mov_b32 m0, s51
	s_nop 0
	global_load_lds_dwordx4 v[228:229], off
	s_waitcnt vmcnt(8)
	s_waitcnt lgkmcnt(0)
	s_barrier
	s_setprio 1
	s_waitcnt lgkmcnt(0)
	v_mfma_f32_16x16x32_bf16 v[126:129], v[130:133], v[190:193], v[126:129]
	v_mfma_f32_16x16x32_bf16 v[122:125], v[166:169], v[190:193], v[122:125]
	v_mfma_f32_16x16x32_bf16 v[110:113], v[130:133], v[198:201], v[110:113]
	v_mfma_f32_16x16x32_bf16 v[106:109], v[166:169], v[198:201], v[106:109]
	v_mfma_f32_16x16x32_bf16 v[94:97], v[130:133], v[206:209], v[94:97]
	v_mfma_f32_16x16x32_bf16 v[90:93], v[166:169], v[206:209], v[90:93]
	v_mfma_f32_16x16x32_bf16 v[78:81], v[130:133], v[214:217], v[78:81]
	v_mfma_f32_16x16x32_bf16 v[74:77], v[166:169], v[214:217], v[74:77]
	v_mfma_f32_16x16x32_bf16 v[126:129], v[152:155], v[194:197], v[126:129]
	v_mfma_f32_16x16x32_bf16 v[122:125], v[170:173], v[194:197], v[122:125]
	v_mfma_f32_16x16x32_bf16 v[110:113], v[152:155], v[202:205], v[110:113]
	v_mfma_f32_16x16x32_bf16 v[106:109], v[170:173], v[202:205], v[106:109]
	v_mfma_f32_16x16x32_bf16 v[94:97], v[152:155], v[210:213], v[94:97]
	v_mfma_f32_16x16x32_bf16 v[90:93], v[170:173], v[210:213], v[90:93]
	v_mfma_f32_16x16x32_bf16 v[78:81], v[152:155], v[218:221], v[78:81]
	v_mfma_f32_16x16x32_bf16 v[74:77], v[170:173], v[218:221], v[74:77]
	s_setprio 0
	s_setprio 1
	v_mfma_f32_16x16x32_bf16 v[118:121], v[174:177], v[190:193], v[118:121]
	v_mfma_f32_16x16x32_bf16 v[114:117], v[182:185], v[190:193], v[114:117]
	v_mfma_f32_16x16x32_bf16 v[102:105], v[174:177], v[198:201], v[102:105]
	v_mfma_f32_16x16x32_bf16 v[98:101], v[182:185], v[198:201], v[98:101]
	v_mfma_f32_16x16x32_bf16 v[86:89], v[174:177], v[206:209], v[86:89]
	v_mfma_f32_16x16x32_bf16 v[82:85], v[182:185], v[206:209], v[82:85]
	v_mfma_f32_16x16x32_bf16 v[70:73], v[174:177], v[214:217], v[70:73]
	v_mfma_f32_16x16x32_bf16 v[66:69], v[182:185], v[214:217], v[66:69]
	v_mfma_f32_16x16x32_bf16 v[118:121], v[178:181], v[194:197], v[118:121]
	v_mfma_f32_16x16x32_bf16 v[114:117], v[186:189], v[194:197], v[114:117]
	v_mfma_f32_16x16x32_bf16 v[102:105], v[178:181], v[202:205], v[102:105]
	v_mfma_f32_16x16x32_bf16 v[98:101], v[186:189], v[202:205], v[98:101]
	v_mfma_f32_16x16x32_bf16 v[86:89], v[178:181], v[210:213], v[86:89]
	v_mfma_f32_16x16x32_bf16 v[82:85], v[186:189], v[210:213], v[82:85]
	v_mfma_f32_16x16x32_bf16 v[70:73], v[178:181], v[218:221], v[70:73]
	s_barrier
; #define PG8_STAGE(bufoff, gbase, voff) do { _Pragma("unroll") for (int _i = 0; _i < 2; ++_i) \
;         __builtin_amdgcn_global_load_lds((const unsigned*)((const char*)(gbase) + (voff)[_i]), (PG8_LAS unsigned*)(lds + (bufoff) + ldsw + _i * 8192), 16, 0, 0); } while (0)
; #define PG8_LDA(dst, b, h) do { _Pragma("unroll") for (int m = 0; m < 4; ++m) _Pragma("unroll") for (int k = 0; k < 2; ++k) dst[m][k] = *(const PG8_LAS bf16x8*)(lds + PG8_SA(b, h) + aoff + m * 2048 + k * 1024); } while (0)
; #define PG8_MMA(ai, bj, At, Bt) do { __builtin_amdgcn_s_setprio(1); _Pragma("unroll") for (int m = 0; m < 4; ++m) _Pragma("unroll") for (int n = 0; n < 2; ++n) _Pragma("unroll") for (int k = 0; k < 2; ++k) \
;         acc[ai][bj][m][n] = __builtin_amdgcn_mfma_f32_16x16x32_bf16(Bt[n][k], At[m][k], acc[ai][bj][m][n], 0, 0, 0); __builtin_amdgcn_s_setprio(0); } while (0)
; #define PG8_WAIT_V(n) asm volatile("s_waitcnt vmcnt(" #n ")" ::: "memory")
; #define PG8_WAIT_L(n) asm volatile("s_waitcnt lgkmcnt(" #n ")" ::: "memory")
; #define PG8_BAR __builtin_amdgcn_s_barrier()
; #define PG8_SCHED __builtin_amdgcn_sched_barrier(0)
; template <class Epi, class Sched, bool ALIGN_EPI = false, bool SP2 = false>
; __device__ __forceinline__ void gemm_phase(PG8_LAS unsigned char* lds, const Gemm g, const Sched& S, const Epi& E) {
;     ...
;             PG8_LDA(At, 1, 1); PG8_STAGE(PG8_SB(1, 0), b3, voffB); PG8_STAGE(PG8_SB(1, 1), b3 + hstep, voffB); PG8_STAGE(PG8_SA(1, 0), a3, voffA);
;             PG8_WAIT_V(8); PG8_WAIT_L(0); PG8_BAR; PG8_MMA(1, 0, At, B0); PG8_MMA(1, 1, At, B1); PG8_BAR; PG8_SCHED;
;     ...
;         if constexpr (ALIGN_EPI) { if (wr == 0) PG8_BAR; }
	v_mfma_f32_16x16x32_bf16 v[66:69], v[186:189], v[218:221], v[66:69]
	s_setprio 0
	s_add_i32 s44, s61, s33
	v_lshl_add_u64 v[162:163], v[162:163], 0, s[12:13]
	s_mov_b32 m0, s44
	ds_read_b128 v[190:193], v161 offset:49152
	ds_read_b128 v[194:197], v161 offset:50176
	ds_read_b128 v[198:201], v161 offset:51200
	ds_read_b128 v[202:205], v161 offset:52224
	ds_read_b128 v[206:209], v161 offset:53248
	ds_read_b128 v[210:213], v161 offset:54272
	ds_read_b128 v[214:217], v161 offset:55296
	ds_read_b128 v[218:221], v161 offset:56320
	global_load_lds_dwordx4 v[162:163], off
	s_add_i32 m0, s44, 0x2000
	s_add_u32 s42, s42, 0x40080
	v_lshl_add_u64 v[162:163], v[222:223], 0, s[12:13]
	s_addc_u32 s43, s43, 0
	s_add_i32 s44, s62, s33
	global_load_lds_dwordx4 v[162:163], off
	v_lshl_add_u64 v[162:163], s[42:43], 0, v[136:137]
	s_mov_b32 m0, s44
	s_nop 0
	global_load_lds_dwordx4 v[162:163], off
	v_lshl_add_u64 v[162:163], s[42:43], 0, v[140:141]
	s_add_i32 m0, s44, 0x2000
	s_nop 0
	global_load_lds_dwordx4 v[162:163], off
	v_lshl_add_u64 v[162:163], v[224:225], 0, s[12:13]
	s_mov_b32 m0, s52
	s_nop 0
	global_load_lds_dwordx4 v[162:163], off
	v_lshl_add_u64 v[162:163], v[226:227], 0, s[12:13]
	s_mov_b32 m0, s53
	s_nop 0
	global_load_lds_dwordx4 v[162:163], off
	s_waitcnt vmcnt(8)
	s_waitcnt lgkmcnt(0)
	s_barrier
	s_setprio 1
	s_waitcnt lgkmcnt(0)
	v_mfma_f32_16x16x32_bf16 v[62:65], v[130:133], v[190:193], v[62:65]
	v_mfma_f32_16x16x32_bf16 v[58:61], v[166:169], v[190:193], v[58:61]
	v_mfma_f32_16x16x32_bf16 v[46:49], v[130:133], v[198:201], v[46:49]
	v_mfma_f32_16x16x32_bf16 v[42:45], v[166:169], v[198:201], v[42:45]
	v_mfma_f32_16x16x32_bf16 v[30:33], v[130:133], v[206:209], v[30:33]
	v_mfma_f32_16x16x32_bf16 v[26:29], v[166:169], v[206:209], v[26:29]
	v_mfma_f32_16x16x32_bf16 v[14:17], v[130:133], v[214:217], v[14:17]
	v_mfma_f32_16x16x32_bf16 v[10:13], v[166:169], v[214:217], v[10:13]
	v_mfma_f32_16x16x32_bf16 v[62:65], v[152:155], v[194:197], v[62:65]
	v_mfma_f32_16x16x32_bf16 v[58:61], v[170:173], v[194:197], v[58:61]
	v_mfma_f32_16x16x32_bf16 v[46:49], v[152:155], v[202:205], v[46:49]
	v_mfma_f32_16x16x32_bf16 v[42:45], v[170:173], v[202:205], v[42:45]
	v_mfma_f32_16x16x32_bf16 v[30:33], v[152:155], v[210:213], v[30:33]
	v_mfma_f32_16x16x32_bf16 v[26:29], v[170:173], v[210:213], v[26:29]
	v_mfma_f32_16x16x32_bf16 v[14:17], v[152:155], v[218:221], v[14:17]
	v_mfma_f32_16x16x32_bf16 v[10:13], v[170:173], v[218:221], v[10:13]
	s_setprio 0
	s_setprio 1
	v_mfma_f32_16x16x32_bf16 v[54:57], v[174:177], v[190:193], v[54:57]
	v_mfma_f32_16x16x32_bf16 v[50:53], v[182:185], v[190:193], v[50:53]
	v_mfma_f32_16x16x32_bf16 v[38:41], v[174:177], v[198:201], v[38:41]
	v_mfma_f32_16x16x32_bf16 v[34:37], v[182:185], v[198:201], v[34:37]
	v_mfma_f32_16x16x32_bf16 v[22:25], v[174:177], v[206:209], v[22:25]
	v_mfma_f32_16x16x32_bf16 v[18:21], v[182:185], v[206:209], v[18:21]
	v_mfma_f32_16x16x32_bf16 v[6:9], v[174:177], v[214:217], v[6:9]
	v_mfma_f32_16x16x32_bf16 v[2:5], v[182:185], v[214:217], v[2:5]
	v_mfma_f32_16x16x32_bf16 v[54:57], v[178:181], v[194:197], v[54:57]
	v_mfma_f32_16x16x32_bf16 v[50:53], v[186:189], v[194:197], v[50:53]
	v_mfma_f32_16x16x32_bf16 v[38:41], v[178:181], v[202:205], v[38:41]
	v_mfma_f32_16x16x32_bf16 v[34:37], v[186:189], v[202:205], v[34:37]
	v_mfma_f32_16x16x32_bf16 v[22:25], v[178:181], v[210:213], v[22:25]
	v_mfma_f32_16x16x32_bf16 v[18:21], v[186:189], v[210:213], v[18:21]
	v_mfma_f32_16x16x32_bf16 v[6:9], v[178:181], v[218:221], v[6:9]
	s_barrier
	v_mfma_f32_16x16x32_bf16 v[2:5], v[186:189], v[218:221], v[2:5]
	s_setprio 0
	s_add_i32 s47, s47, 2
	s_add_u32 s4, s4, 0x100
	s_addc_u32 s5, s5, 0
	s_add_u32 s25, s25, 0x100
	s_addc_u32 s46, s46, 0
	s_cmp_gt_u32 s47, 13
	s_cbranch_scc0 .LBB0_811
	s_and_b64 vcc, exec, s[14:15]
	s_cbranch_vccz .LBB0_814
	s_barrier

; #define PG8_STAGE(bufoff, gbase, voff) do { _Pragma("unroll") for (int _i = 0; _i < 2; ++_i) \
;         __builtin_amdgcn_global_load_lds((const unsigned*)((const char*)(gbase) + (voff)[_i]), (PG8_LAS unsigned*)(lds + (bufoff) + ldsw + _i * 8192), 16, 0, 0); } while (0)
; #define PG8_LDA(dst, b, h) do { _Pragma("unroll") for (int m = 0; m < 4; ++m) _Pragma("unroll") for (int k = 0; k < 2; ++k) dst[m][k] = *(const PG8_LAS bf16x8*)(lds + PG8_SA(b, h) + aoff + m * 2048 + k * 1024); } while (0)
; #define PG8_LDB(dst, b, h) do { _Pragma("unroll") for (int n = 0; n < 2; ++n) _Pragma("unroll") for (int k = 0; k < 2; ++k) dst[n][k] = *(const PG8_LAS bf16x8*)(lds + PG8_SB(b, h) + boff + n * 2048 + k * 1024); } while (0)
; #define PG8_MMA(ai, bj, At, Bt) do { __builtin_amdgcn_s_setprio(1); _Pragma("unroll") for (int m = 0; m < 4; ++m) _Pragma("unroll") for (int n = 0; n < 2; ++n) _Pragma("unroll") for (int k = 0; k < 2; ++k) \
;         acc[ai][bj][m][n] = __builtin_amdgcn_mfma_f32_16x16x32_bf16(Bt[n][k], At[m][k], acc[ai][bj][m][n], 0, 0, 0); __builtin_amdgcn_s_setprio(0); } while (0)
; #define PG8_WAIT_V(n) asm volatile("s_waitcnt vmcnt(" #n ")" ::: "memory")
; #define PG8_WAIT_L(n) asm volatile("s_waitcnt lgkmcnt(" #n ")" ::: "memory")
; #define PG8_BAR __builtin_amdgcn_s_barrier()
; #define PG8_SCHED __builtin_amdgcn_sched_barrier(0)
; template <class Epi, class Sched, bool ALIGN_EPI = false, bool SP2 = false>
; __device__ __forceinline__ void gemm_phase(PG8_LAS unsigned char* lds, const Gemm g, const Sched& S, const Epi& E) {
;     ...
;             PG8_LDB(B0, 0, 0); PG8_LDB(B1, 0, 1); PG8_SCHED; PG8_LDA(At, 0, 0); PG8_STAGE(PG8_SA(1, 1), a1 + hstep, voffA);
;             PG8_WAIT_V(8); PG8_WAIT_L(0); PG8_BAR; PG8_MMA(0, 0, At, B0); PG8_MMA(0, 1, At, B1); PG8_BAR; PG8_SCHED;
;             PG8_LDA(At, 0, 1); PG8_STAGE(PG8_SB(0, 0), b2, voffB); PG8_STAGE(PG8_SB(0, 1), b2 + hstep, voffB); PG8_STAGE(PG8_SA(0, 0), a2, voffA);
.LBB0_884:
	ds_read_b128 v[130:133], v159
	ds_read_b128 v[146:149], v159 offset:1024
	ds_read_b128 v[150:153], v159 offset:2048
	ds_read_b128 v[162:165], v159 offset:3072
	ds_read_b128 v[166:169], v160
	ds_read_b128 v[170:173], v160 offset:1024
	ds_read_b128 v[174:177], v160 offset:2048
	ds_read_b128 v[178:181], v160 offset:3072
	s_add_u32 s46, s44, 0xfffc0080
	s_addc_u32 s47, s45, -1
	s_cmp_eq_u32 s60, 12
	s_cselect_b32 s49, s35, s47
	s_cselect_b32 s48, s34, s46
	s_cselect_b32 s47, s17, s59
	s_cselect_b32 s46, s19, s58
	v_lshl_add_u64 v[214:215], s[44:45], 0, v[142:143]
	s_add_i32 m0, s50, 0xc000
	ds_read_b128 v[182:185], v161
	ds_read_b128 v[186:189], v161 offset:1024
	ds_read_b128 v[190:193], v161 offset:2048
	ds_read_b128 v[194:197], v161 offset:3072
	ds_read_b128 v[198:201], v161 offset:4096
	ds_read_b128 v[202:205], v161 offset:5120
	ds_read_b128 v[206:209], v161 offset:6144
	ds_read_b128 v[210:213], v161 offset:7168
	global_load_lds_dwordx4 v[214:215], off
	v_lshl_add_u64 v[214:215], s[44:45], 0, v[144:145]
	s_add_i32 m0, s50, 0xe000
	s_nop 0
	global_load_lds_dwordx4 v[214:215], off
	s_waitcnt vmcnt(8)
	s_waitcnt lgkmcnt(0)
	s_barrier
	s_setprio 1
	s_waitcnt lgkmcnt(0)
	v_mfma_f32_16x16x32_bf16 v[126:129], v[130:133], v[182:185], v[126:129]
	v_mfma_f32_16x16x32_bf16 v[122:125], v[150:153], v[182:185], v[122:125]
	v_mfma_f32_16x16x32_bf16 v[110:113], v[130:133], v[190:193], v[110:113]
	v_mfma_f32_16x16x32_bf16 v[106:109], v[150:153], v[190:193], v[106:109]
	v_mfma_f32_16x16x32_bf16 v[94:97], v[130:133], v[198:201], v[94:97]
	v_mfma_f32_16x16x32_bf16 v[90:93], v[150:153], v[198:201], v[90:93]
	v_mfma_f32_16x16x32_bf16 v[78:81], v[130:133], v[206:209], v[78:81]
	v_mfma_f32_16x16x32_bf16 v[74:77], v[150:153], v[206:209], v[74:77]
	v_mfma_f32_16x16x32_bf16 v[126:129], v[146:149], v[186:189], v[126:129]
	v_mfma_f32_16x16x32_bf16 v[122:125], v[162:165], v[186:189], v[122:125]
	v_mfma_f32_16x16x32_bf16 v[110:113], v[146:149], v[194:197], v[110:113]
	v_mfma_f32_16x16x32_bf16 v[106:109], v[162:165], v[194:197], v[106:109]
	v_mfma_f32_16x16x32_bf16 v[94:97], v[146:149], v[202:205], v[94:97]
	v_mfma_f32_16x16x32_bf16 v[90:93], v[162:165], v[202:205], v[90:93]
	v_mfma_f32_16x16x32_bf16 v[78:81], v[146:149], v[210:213], v[78:81]
	v_mfma_f32_16x16x32_bf16 v[74:77], v[162:165], v[210:213], v[74:77]
	s_setprio 0
	s_setprio 1
	v_mfma_f32_16x16x32_bf16 v[118:121], v[166:169], v[182:185], v[118:121]
	v_mfma_f32_16x16x32_bf16 v[114:117], v[174:177], v[182:185], v[114:117]
	v_mfma_f32_16x16x32_bf16 v[102:105], v[166:169], v[190:193], v[102:105]
	v_mfma_f32_16x16x32_bf16 v[98:101], v[174:177], v[190:193], v[98:101]
	v_mfma_f32_16x16x32_bf16 v[86:89], v[166:169], v[198:201], v[86:89]
	v_mfma_f32_16x16x32_bf16 v[82:85], v[174:177], v[198:201], v[82:85]
	v_mfma_f32_16x16x32_bf16 v[70:73], v[166:169], v[206:209], v[70:73]
	v_mfma_f32_16x16x32_bf16 v[66:69], v[174:177], v[206:209], v[66:69]
	v_mfma_f32_16x16x32_bf16 v[118:121], v[170:173], v[186:189], v[118:121]
	v_mfma_f32_16x16x32_bf16 v[114:117], v[178:181], v[186:189], v[114:117]
	v_mfma_f32_16x16x32_bf16 v[102:105], v[170:173], v[194:197], v[102:105]
	v_mfma_f32_16x16x32_bf16 v[98:101], v[178:181], v[194:197], v[98:101]
	v_mfma_f32_16x16x32_bf16 v[86:89], v[170:173], v[202:205], v[86:89]
	v_mfma_f32_16x16x32_bf16 v[82:85], v[178:181], v[202:205], v[82:85]
	v_mfma_f32_16x16x32_bf16 v[70:73], v[170:173], v[210:213], v[70:73]
	s_barrier
	v_mfma_f32_16x16x32_bf16 v[66:69], v[178:181], v[210:213], v[66:69]
	s_setprio 0
	s_add_i32 s61, s56, s33
	v_lshl_add_u64 v[214:215], s[46:47], 0, v[138:139]
	s_mov_b32 m0, s61
	ds_read_b128 v[182:185], v161 offset:16384
	ds_read_b128 v[186:189], v161 offset:17408
	ds_read_b128 v[190:193], v161 offset:18432
	ds_read_b128 v[194:197], v161 offset:19456
	ds_read_b128 v[198:201], v161 offset:20480
	ds_read_b128 v[202:205], v161 offset:21504
	ds_read_b128 v[206:209], v161 offset:22528
	ds_read_b128 v[210:213], v161 offset:23552
	global_load_lds_dwordx4 v[214:215], off
	s_add_i32 m0, s61, 0x2000
	s_add_u32 s62, s46, 0x40000
	v_lshl_add_u64 v[216:217], s[46:47], 0, v[134:135]
	s_addc_u32 s63, s47, 0
	s_add_i32 s61, s57, s33
	global_load_lds_dwordx4 v[216:217], off
	v_lshl_add_u64 v[218:219], s[62:63], 0, v[138:139]
	s_mov_b32 m0, s61
	v_lshl_add_u64 v[220:221], s[48:49], 0, v[136:137]
	global_load_lds_dwordx4 v[218:219], off
	v_lshl_add_u64 v[218:219], s[62:63], 0, v[134:135]
	s_add_i32 m0, s61, 0x2000
	s_nop 0
	global_load_lds_dwordx4 v[218:219], off
	v_lshl_add_u64 v[218:219], s[48:49], 0, v[140:141]
	s_mov_b32 m0, s50
	s_nop 0
	global_load_lds_dwordx4 v[218:219], off
	s_mov_b32 m0, s51
	s_nop 0
	global_load_lds_dwordx4 v[220:221], off
	s_waitcnt vmcnt(8)
	s_waitcnt lgkmcnt(0)
	s_barrier
; #define PG8_STAGE(bufoff, gbase, voff) do { _Pragma("unroll") for (int _i = 0; _i < 2; ++_i) \
;         __builtin_amdgcn_global_load_lds((const unsigned*)((const char*)(gbase) + (voff)[_i]), (PG8_LAS unsigned*)(lds + (bufoff) + ldsw + _i * 8192), 16, 0, 0); } while (0)
; #define PG8_LDA(dst, b, h) do { _Pragma("unroll") for (int m = 0; m < 4; ++m) _Pragma("unroll") for (int k = 0; k < 2; ++k) dst[m][k] = *(const PG8_LAS bf16x8*)(lds + PG8_SA(b, h) + aoff + m * 2048 + k * 1024); } while (0)
; #define PG8_LDB(dst, b, h) do { _Pragma("unroll") for (int n = 0; n < 2; ++n) _Pragma("unroll") for (int k = 0; k < 2; ++k) dst[n][k] = *(const PG8_LAS bf16x8*)(lds + PG8_SB(b, h) + boff + n * 2048 + k * 1024); } while (0)
; #define PG8_MMA(ai, bj, At, Bt) do { __builtin_amdgcn_s_setprio(1); _Pragma("unroll") for (int m = 0; m < 4; ++m) _Pragma("unroll") for (int n = 0; n < 2; ++n) _Pragma("unroll") for (int k = 0; k < 2; ++k) \
;         acc[ai][bj][m][n] = __builtin_amdgcn_mfma_f32_16x16x32_bf16(Bt[n][k], At[m][k], acc[ai][bj][m][n], 0, 0, 0); __builtin_amdgcn_s_setprio(0); } while (0)
; #define PG8_WAIT_V(n) asm volatile("s_waitcnt vmcnt(" #n ")" ::: "memory")
; #define PG8_WAIT_L(n) asm volatile("s_waitcnt lgkmcnt(" #n ")" ::: "memory")
; #define PG8_BAR __builtin_amdgcn_s_barrier()
; #define PG8_SCHED __builtin_amdgcn_sched_barrier(0)
; template <class Epi, class Sched, bool ALIGN_EPI = false, bool SP2 = false>
; __device__ __forceinline__ void gemm_phase(PG8_LAS unsigned char* lds, const Gemm g, const Sched& S, const Epi& E) {
;     ...
;             PG8_WAIT_V(8); PG8_WAIT_L(0); PG8_BAR; PG8_MMA(1, 0, At, B0); PG8_MMA(1, 1, At, B1); PG8_BAR; PG8_SCHED;
;             PG8_LDB(B0, 1, 0); PG8_LDB(B1, 1, 1); PG8_SCHED; PG8_LDA(At, 1, 0); PG8_STAGE(PG8_SA(0, 1), a2 + hstep, voffA);
;             PG8_WAIT_V(8); PG8_WAIT_L(0); PG8_BAR; PG8_MMA(0, 0, At, B0); PG8_MMA(0, 1, At, B1); PG8_BAR; PG8_SCHED;
	s_setprio 1
	s_waitcnt lgkmcnt(0)
	v_mfma_f32_16x16x32_bf16 v[62:65], v[130:133], v[182:185], v[62:65]
	v_mfma_f32_16x16x32_bf16 v[58:61], v[150:153], v[182:185], v[58:61]
	v_mfma_f32_16x16x32_bf16 v[46:49], v[130:133], v[190:193], v[46:49]
	v_mfma_f32_16x16x32_bf16 v[42:45], v[150:153], v[190:193], v[42:45]
	v_mfma_f32_16x16x32_bf16 v[30:33], v[130:133], v[198:201], v[30:33]
	v_mfma_f32_16x16x32_bf16 v[26:29], v[150:153], v[198:201], v[26:29]
	v_mfma_f32_16x16x32_bf16 v[14:17], v[130:133], v[206:209], v[14:17]
	v_mfma_f32_16x16x32_bf16 v[10:13], v[150:153], v[206:209], v[10:13]
	v_mfma_f32_16x16x32_bf16 v[62:65], v[146:149], v[186:189], v[62:65]
	v_mfma_f32_16x16x32_bf16 v[58:61], v[162:165], v[186:189], v[58:61]
	v_mfma_f32_16x16x32_bf16 v[46:49], v[146:149], v[194:197], v[46:49]
	v_mfma_f32_16x16x32_bf16 v[42:45], v[162:165], v[194:197], v[42:45]
	v_mfma_f32_16x16x32_bf16 v[30:33], v[146:149], v[202:205], v[30:33]
	v_mfma_f32_16x16x32_bf16 v[26:29], v[162:165], v[202:205], v[26:29]
	v_mfma_f32_16x16x32_bf16 v[14:17], v[146:149], v[210:213], v[14:17]
	v_mfma_f32_16x16x32_bf16 v[10:13], v[162:165], v[210:213], v[10:13]
	s_setprio 0
	s_setprio 1
	v_mfma_f32_16x16x32_bf16 v[54:57], v[166:169], v[182:185], v[54:57]
	v_mfma_f32_16x16x32_bf16 v[50:53], v[174:177], v[182:185], v[50:53]
	v_mfma_f32_16x16x32_bf16 v[38:41], v[166:169], v[190:193], v[38:41]
	v_mfma_f32_16x16x32_bf16 v[34:37], v[174:177], v[190:193], v[34:37]
	v_mfma_f32_16x16x32_bf16 v[22:25], v[166:169], v[198:201], v[22:25]
	v_mfma_f32_16x16x32_bf16 v[18:21], v[174:177], v[198:201], v[18:21]
	v_mfma_f32_16x16x32_bf16 v[6:9], v[166:169], v[206:209], v[6:9]
	v_mfma_f32_16x16x32_bf16 v[2:5], v[174:177], v[206:209], v[2:5]
	v_mfma_f32_16x16x32_bf16 v[54:57], v[170:173], v[186:189], v[54:57]
	v_mfma_f32_16x16x32_bf16 v[50:53], v[178:181], v[186:189], v[50:53]
	v_mfma_f32_16x16x32_bf16 v[38:41], v[170:173], v[194:197], v[38:41]
	v_mfma_f32_16x16x32_bf16 v[34:37], v[178:181], v[194:197], v[34:37]
	v_mfma_f32_16x16x32_bf16 v[22:25], v[170:173], v[202:205], v[22:25]
	v_mfma_f32_16x16x32_bf16 v[18:21], v[178:181], v[202:205], v[18:21]
	v_mfma_f32_16x16x32_bf16 v[6:9], v[170:173], v[210:213], v[6:9]
	s_barrier
	v_mfma_f32_16x16x32_bf16 v[2:5], v[178:181], v[210:213], v[2:5]
	s_setprio 0
	s_add_i32 s61, 0, 0x18000
	s_add_i32 s62, 0, 0x1c000
	v_add_u32_e32 v162, s61, v155
	v_add_u32_e32 v178, s62, v155
	ds_read_b128 v[130:133], v162
	ds_read_b128 v[146:149], v162 offset:1024
	ds_read_b128 v[150:153], v162 offset:2048
	ds_read_b128 v[162:165], v162 offset:3072
	ds_read_b128 v[166:169], v178
	ds_read_b128 v[170:173], v178 offset:1024
	ds_read_b128 v[174:177], v178 offset:2048
	ds_read_b128 v[178:181], v178 offset:3072
	s_add_u32 s48, s48, 0x40000
	s_addc_u32 s49, s49, 0
	s_mov_b32 m0, s52
	v_lshl_add_u64 v[222:223], s[48:49], 0, v[140:141]
	ds_read_b128 v[182:185], v161 offset:32768
	ds_read_b128 v[186:189], v161 offset:33792
	ds_read_b128 v[190:193], v161 offset:34816
	ds_read_b128 v[194:197], v161 offset:35840
	ds_read_b128 v[198:201], v161 offset:36864
	ds_read_b128 v[202:205], v161 offset:37888
	ds_read_b128 v[206:209], v161 offset:38912
	ds_read_b128 v[210:213], v161 offset:39936
	global_load_lds_dwordx4 v[222:223], off
	v_lshl_add_u64 v[222:223], s[48:49], 0, v[136:137]
	s_mov_b32 m0, s53
	s_nop 0
	global_load_lds_dwordx4 v[222:223], off
	s_waitcnt vmcnt(8)
	s_waitcnt lgkmcnt(0)
	s_barrier
	s_setprio 1
	s_waitcnt lgkmcnt(0)
	v_mfma_f32_16x16x32_bf16 v[126:129], v[130:133], v[182:185], v[126:129]
	v_mfma_f32_16x16x32_bf16 v[122:125], v[150:153], v[182:185], v[122:125]
	v_mfma_f32_16x16x32_bf16 v[110:113], v[130:133], v[190:193], v[110:113]
	v_mfma_f32_16x16x32_bf16 v[106:109], v[150:153], v[190:193], v[106:109]
	v_mfma_f32_16x16x32_bf16 v[94:97], v[130:133], v[198:201], v[94:97]
	v_mfma_f32_16x16x32_bf16 v[90:93], v[150:153], v[198:201], v[90:93]
	v_mfma_f32_16x16x32_bf16 v[78:81], v[130:133], v[206:209], v[78:81]
	v_mfma_f32_16x16x32_bf16 v[74:77], v[150:153], v[206:209], v[74:77]
	v_mfma_f32_16x16x32_bf16 v[126:129], v[146:149], v[186:189], v[126:129]
	v_mfma_f32_16x16x32_bf16 v[122:125], v[162:165], v[186:189], v[122:125]
	v_mfma_f32_16x16x32_bf16 v[110:113], v[146:149], v[194:197], v[110:113]
	v_mfma_f32_16x16x32_bf16 v[106:109], v[162:165], v[194:197], v[106:109]
	v_mfma_f32_16x16x32_bf16 v[94:97], v[146:149], v[202:205], v[94:97]
	v_mfma_f32_16x16x32_bf16 v[90:93], v[162:165], v[202:205], v[90:93]
	v_mfma_f32_16x16x32_bf16 v[78:81], v[146:149], v[210:213], v[78:81]
	v_mfma_f32_16x16x32_bf16 v[74:77], v[162:165], v[210:213], v[74:77]
	s_setprio 0
	s_setprio 1
	v_mfma_f32_16x16x32_bf16 v[118:121], v[166:169], v[182:185], v[118:121]
	v_mfma_f32_16x16x32_bf16 v[114:117], v[174:177], v[182:185], v[114:117]
	v_mfma_f32_16x16x32_bf16 v[102:105], v[166:169], v[190:193], v[102:105]
	v_mfma_f32_16x16x32_bf16 v[98:101], v[174:177], v[190:193], v[98:101]
	v_mfma_f32_16x16x32_bf16 v[86:89], v[166:169], v[198:201], v[86:89]
	v_mfma_f32_16x16x32_bf16 v[82:85], v[174:177], v[198:201], v[82:85]
	v_mfma_f32_16x16x32_bf16 v[70:73], v[166:169], v[206:209], v[70:73]
	v_mfma_f32_16x16x32_bf16 v[66:69], v[174:177], v[206:209], v[66:69]
	v_mfma_f32_16x16x32_bf16 v[118:121], v[170:173], v[186:189], v[118:121]
	v_mfma_f32_16x16x32_bf16 v[114:117], v[178:181], v[186:189], v[114:117]
	v_mfma_f32_16x16x32_bf16 v[102:105], v[170:173], v[194:197], v[102:105]
	v_mfma_f32_16x16x32_bf16 v[98:101], v[178:181], v[194:197], v[98:101]
	v_mfma_f32_16x16x32_bf16 v[86:89], v[170:173], v[202:205], v[86:89]
	v_mfma_f32_16x16x32_bf16 v[82:85], v[178:181], v[202:205], v[82:85]
	v_mfma_f32_16x16x32_bf16 v[70:73], v[170:173], v[210:213], v[70:73]
	s_barrier
; #define PG8_STAGE(bufoff, gbase, voff) do { _Pragma("unroll") for (int _i = 0; _i < 2; ++_i) \
;         __builtin_amdgcn_global_load_lds((const unsigned*)((const char*)(gbase) + (voff)[_i]), (PG8_LAS unsigned*)(lds + (bufoff) + ldsw + _i * 8192), 16, 0, 0); } while (0)
; #define PG8_LDA(dst, b, h) do { _Pragma("unroll") for (int m = 0; m < 4; ++m) _Pragma("unroll") for (int k = 0; k < 2; ++k) dst[m][k] = *(const PG8_LAS bf16x8*)(lds + PG8_SA(b, h) + aoff + m * 2048 + k * 1024); } while (0)
; #define PG8_MMA(ai, bj, At, Bt) do { __builtin_amdgcn_s_setprio(1); _Pragma("unroll") for (int m = 0; m < 4; ++m) _Pragma("unroll") for (int n = 0; n < 2; ++n) _Pragma("unroll") for (int k = 0; k < 2; ++k) \
;         acc[ai][bj][m][n] = __builtin_amdgcn_mfma_f32_16x16x32_bf16(Bt[n][k], At[m][k], acc[ai][bj][m][n], 0, 0, 0); __builtin_amdgcn_s_setprio(0); } while (0)
; #define PG8_WAIT_V(n) asm volatile("s_waitcnt vmcnt(" #n ")" ::: "memory")
; #define PG8_WAIT_L(n) asm volatile("s_waitcnt lgkmcnt(" #n ")" ::: "memory")
; #define PG8_BAR __builtin_amdgcn_s_barrier()
; #define PG8_SCHED __builtin_amdgcn_sched_barrier(0)
; template <class Epi, class Sched, bool ALIGN_EPI = false, bool SP2 = false>
; __device__ __forceinline__ void gemm_phase(PG8_LAS unsigned char* lds, const Gemm g, const Sched& S, const Epi& E) {
;     ...
;             PG8_LDA(At, 1, 1); PG8_STAGE(PG8_SB(1, 0), b3, voffB); PG8_STAGE(PG8_SB(1, 1), b3 + hstep, voffB); PG8_STAGE(PG8_SA(1, 0), a3, voffA);
;             PG8_WAIT_V(8); PG8_WAIT_L(0); PG8_BAR; PG8_MMA(1, 0, At, B0); PG8_MMA(1, 1, At, B1); PG8_BAR; PG8_SCHED;
;     ...
;         if constexpr (ALIGN_EPI) { if (wr == 0) PG8_BAR; }
	v_mfma_f32_16x16x32_bf16 v[66:69], v[178:181], v[210:213], v[66:69]
	s_setprio 0
	s_add_i32 s48, s61, s33
	v_lshl_add_u64 v[214:215], v[214:215], 0, s[12:13]
	s_mov_b32 m0, s48
	ds_read_b128 v[182:185], v161 offset:49152
	ds_read_b128 v[186:189], v161 offset:50176
	ds_read_b128 v[190:193], v161 offset:51200
	ds_read_b128 v[194:197], v161 offset:52224
	ds_read_b128 v[198:201], v161 offset:53248
	ds_read_b128 v[202:205], v161 offset:54272
	ds_read_b128 v[206:209], v161 offset:55296
	ds_read_b128 v[210:213], v161 offset:56320
	global_load_lds_dwordx4 v[214:215], off
	s_add_i32 m0, s48, 0x2000
	s_add_u32 s46, s46, 0x40080
	v_lshl_add_u64 v[214:215], v[216:217], 0, s[12:13]
	s_addc_u32 s47, s47, 0
	s_add_i32 s48, s62, s33
	global_load_lds_dwordx4 v[214:215], off
	v_lshl_add_u64 v[214:215], s[46:47], 0, v[138:139]
	s_mov_b32 m0, s48
	s_nop 0
	global_load_lds_dwordx4 v[214:215], off
	v_lshl_add_u64 v[214:215], s[46:47], 0, v[134:135]
	s_add_i32 m0, s48, 0x2000
	s_nop 0
	global_load_lds_dwordx4 v[214:215], off
	v_lshl_add_u64 v[214:215], v[218:219], 0, s[12:13]
	s_mov_b32 m0, s54
	s_nop 0
	global_load_lds_dwordx4 v[214:215], off
	v_lshl_add_u64 v[214:215], v[220:221], 0, s[12:13]
	s_mov_b32 m0, s55
	s_nop 0
	global_load_lds_dwordx4 v[214:215], off
	s_waitcnt vmcnt(8)
	s_waitcnt lgkmcnt(0)
	s_barrier
	s_setprio 1
	s_waitcnt lgkmcnt(0)
	v_mfma_f32_16x16x32_bf16 v[62:65], v[130:133], v[182:185], v[62:65]
	v_mfma_f32_16x16x32_bf16 v[58:61], v[150:153], v[182:185], v[58:61]
	v_mfma_f32_16x16x32_bf16 v[46:49], v[130:133], v[190:193], v[46:49]
	v_mfma_f32_16x16x32_bf16 v[42:45], v[150:153], v[190:193], v[42:45]
	v_mfma_f32_16x16x32_bf16 v[30:33], v[130:133], v[198:201], v[30:33]
	v_mfma_f32_16x16x32_bf16 v[26:29], v[150:153], v[198:201], v[26:29]
	v_mfma_f32_16x16x32_bf16 v[14:17], v[130:133], v[206:209], v[14:17]
	v_mfma_f32_16x16x32_bf16 v[10:13], v[150:153], v[206:209], v[10:13]
	v_mfma_f32_16x16x32_bf16 v[62:65], v[146:149], v[186:189], v[62:65]
	v_mfma_f32_16x16x32_bf16 v[58:61], v[162:165], v[186:189], v[58:61]
	v_mfma_f32_16x16x32_bf16 v[46:49], v[146:149], v[194:197], v[46:49]
	v_mfma_f32_16x16x32_bf16 v[42:45], v[162:165], v[194:197], v[42:45]
	v_mfma_f32_16x16x32_bf16 v[30:33], v[146:149], v[202:205], v[30:33]
	v_mfma_f32_16x16x32_bf16 v[26:29], v[162:165], v[202:205], v[26:29]
	v_mfma_f32_16x16x32_bf16 v[14:17], v[146:149], v[210:213], v[14:17]
	v_mfma_f32_16x16x32_bf16 v[10:13], v[162:165], v[210:213], v[10:13]
	s_setprio 0
	s_setprio 1
	v_mfma_f32_16x16x32_bf16 v[54:57], v[166:169], v[182:185], v[54:57]
	v_mfma_f32_16x16x32_bf16 v[50:53], v[174:177], v[182:185], v[50:53]
	v_mfma_f32_16x16x32_bf16 v[38:41], v[166:169], v[190:193], v[38:41]
	v_mfma_f32_16x16x32_bf16 v[34:37], v[174:177], v[190:193], v[34:37]
	v_mfma_f32_16x16x32_bf16 v[22:25], v[166:169], v[198:201], v[22:25]
	v_mfma_f32_16x16x32_bf16 v[18:21], v[174:177], v[198:201], v[18:21]
	v_mfma_f32_16x16x32_bf16 v[6:9], v[166:169], v[206:209], v[6:9]
	v_mfma_f32_16x16x32_bf16 v[2:5], v[174:177], v[206:209], v[2:5]
	v_mfma_f32_16x16x32_bf16 v[54:57], v[170:173], v[186:189], v[54:57]
	v_mfma_f32_16x16x32_bf16 v[50:53], v[178:181], v[186:189], v[50:53]
	v_mfma_f32_16x16x32_bf16 v[38:41], v[170:173], v[194:197], v[38:41]
	v_mfma_f32_16x16x32_bf16 v[34:37], v[178:181], v[194:197], v[34:37]
	v_mfma_f32_16x16x32_bf16 v[22:25], v[170:173], v[202:205], v[22:25]
	v_mfma_f32_16x16x32_bf16 v[18:21], v[178:181], v[202:205], v[18:21]
	v_mfma_f32_16x16x32_bf16 v[6:9], v[170:173], v[210:213], v[6:9]
	s_barrier
	v_mfma_f32_16x16x32_bf16 v[2:5], v[178:181], v[210:213], v[2:5]
	s_setprio 0
	s_add_i32 s60, s60, 2
	s_add_u32 s44, s44, 0x100
	s_addc_u32 s45, s45, 0
	s_add_u32 s58, s58, 0x100
	s_addc_u32 s59, s59, 0
	s_cmp_gt_u32 s60, 13
	s_cbranch_scc0 .LBB0_884
	s_and_b64 vcc, exec, s[14:15]
	s_cbranch_vccz .LBB0_887
	s_barrier

; #define PG8_STAGE(bufoff, gbase, voff) do { _Pragma("unroll") for (int _i = 0; _i < 2; ++_i) \
;         __builtin_amdgcn_global_load_lds((const unsigned*)((const char*)(gbase) + (voff)[_i]), (PG8_LAS unsigned*)(lds + (bufoff) + ldsw + _i * 8192), 16, 0, 0); } while (0)
; #define PG8_LDA(dst, b, h) do { _Pragma("unroll") for (int m = 0; m < 4; ++m) _Pragma("unroll") for (int k = 0; k < 2; ++k) dst[m][k] = *(const PG8_LAS bf16x8*)(lds + PG8_SA(b, h) + aoff + m * 2048 + k * 1024); } while (0)
; #define PG8_LDB(dst, b, h) do { _Pragma("unroll") for (int n = 0; n < 2; ++n) _Pragma("unroll") for (int k = 0; k < 2; ++k) dst[n][k] = *(const PG8_LAS bf16x8*)(lds + PG8_SB(b, h) + boff + n * 2048 + k * 1024); } while (0)
; #define PG8_MMA(ai, bj, At, Bt) do { __builtin_amdgcn_s_setprio(1); _Pragma("unroll") for (int m = 0; m < 4; ++m) _Pragma("unroll") for (int n = 0; n < 2; ++n) _Pragma("unroll") for (int k = 0; k < 2; ++k) \
;         acc[ai][bj][m][n] = __builtin_amdgcn_mfma_f32_16x16x32_bf16(Bt[n][k], At[m][k], acc[ai][bj][m][n], 0, 0, 0); __builtin_amdgcn_s_setprio(0); } while (0)
; #define PG8_WAIT_V(n) asm volatile("s_waitcnt vmcnt(" #n ")" ::: "memory")
; #define PG8_WAIT_L(n) asm volatile("s_waitcnt lgkmcnt(" #n ")" ::: "memory")
; #define PG8_BAR __builtin_amdgcn_s_barrier()
; #define PG8_SCHED __builtin_amdgcn_sched_barrier(0)
; template <class Epi, class Sched, bool ALIGN_EPI = false, bool SP2 = false>
; __device__ __forceinline__ void gemm_phase(PG8_LAS unsigned char* lds, const Gemm g, const Sched& S, const Epi& E) {
;     ...
;             PG8_LDB(B0, 0, 0); PG8_LDB(B1, 0, 1); PG8_SCHED; PG8_LDA(At, 0, 0); PG8_STAGE(PG8_SA(1, 1), a1 + hstep, voffA);
;             PG8_WAIT_V(8); PG8_WAIT_L(0); PG8_BAR; PG8_MMA(0, 0, At, B0); PG8_MMA(0, 1, At, B1); PG8_BAR; PG8_SCHED;
;             PG8_LDA(At, 0, 1); PG8_STAGE(PG8_SB(0, 0), b2, voffB); PG8_STAGE(PG8_SB(0, 1), b2 + hstep, voffB); PG8_STAGE(PG8_SA(0, 0), a2, voffA);
.LBB0_968:
	v_add_u32_e32 v162, s45, v148
	v_add_u32_e32 v178, s46, v148
	s_add_u32 s22, s8, s20
	ds_read_b128 v[150:153], v162
	ds_read_b128 v[154:157], v162 offset:1024
	ds_read_b128 v[158:161], v162 offset:2048
	ds_read_b128 v[162:165], v162 offset:3072
	ds_read_b128 v[166:169], v178
	ds_read_b128 v[170:173], v178 offset:1024
	ds_read_b128 v[174:177], v178 offset:2048
	ds_read_b128 v[178:181], v178 offset:3072
	s_addc_u32 s23, s9, s21
	s_add_u32 s22, s22, 0x100
	s_addc_u32 s23, s23, 0
	s_add_u32 s51, s48, s20
	s_addc_u32 s52, s49, s21
	s_cmpk_eq_i32 s20, 0x700
	s_cselect_b32 s25, s19, s23
	s_cselect_b32 s24, s18, s22
	s_cselect_b32 s23, s13, s52
	s_cselect_b32 s22, s15, s51
	v_lshl_add_u64 v[214:215], v[142:143], 0, s[20:21]
	s_add_i32 m0, s5, 0xc000
	ds_read_b128 v[182:185], v149
	ds_read_b128 v[186:189], v149 offset:1024
	ds_read_b128 v[190:193], v149 offset:2048
	ds_read_b128 v[194:197], v149 offset:3072
	ds_read_b128 v[198:201], v149 offset:4096
	ds_read_b128 v[202:205], v149 offset:5120
	ds_read_b128 v[206:209], v149 offset:6144
	ds_read_b128 v[210:213], v149 offset:7168
	global_load_lds_dwordx4 v[214:215], off
	v_lshl_add_u64 v[214:215], v[144:145], 0, s[20:21]
	s_add_i32 m0, s5, 0xe000
	s_nop 0
	global_load_lds_dwordx4 v[214:215], off
	s_waitcnt vmcnt(8)
	s_waitcnt lgkmcnt(0)
	s_barrier
	s_setprio 1
	s_waitcnt lgkmcnt(0)
	v_mfma_f32_16x16x32_bf16 v[126:129], v[150:153], v[182:185], v[126:129]
	v_mfma_f32_16x16x32_bf16 v[122:125], v[158:161], v[182:185], v[122:125]
	v_mfma_f32_16x16x32_bf16 v[114:117], v[150:153], v[190:193], v[114:117]
	v_mfma_f32_16x16x32_bf16 v[106:109], v[158:161], v[190:193], v[106:109]
	v_mfma_f32_16x16x32_bf16 v[98:101], v[150:153], v[198:201], v[98:101]
	v_mfma_f32_16x16x32_bf16 v[90:93], v[158:161], v[198:201], v[90:93]
	v_mfma_f32_16x16x32_bf16 v[82:85], v[150:153], v[206:209], v[82:85]
	v_mfma_f32_16x16x32_bf16 v[74:77], v[158:161], v[206:209], v[74:77]
	v_mfma_f32_16x16x32_bf16 v[126:129], v[154:157], v[186:189], v[126:129]
	v_mfma_f32_16x16x32_bf16 v[122:125], v[162:165], v[186:189], v[122:125]
	v_mfma_f32_16x16x32_bf16 v[114:117], v[154:157], v[194:197], v[114:117]
	v_mfma_f32_16x16x32_bf16 v[106:109], v[162:165], v[194:197], v[106:109]
	v_mfma_f32_16x16x32_bf16 v[98:101], v[154:157], v[202:205], v[98:101]
	v_mfma_f32_16x16x32_bf16 v[90:93], v[162:165], v[202:205], v[90:93]
	v_mfma_f32_16x16x32_bf16 v[82:85], v[154:157], v[210:213], v[82:85]
	v_mfma_f32_16x16x32_bf16 v[74:77], v[162:165], v[210:213], v[74:77]
	s_setprio 0
	s_setprio 1
	v_mfma_f32_16x16x32_bf16 v[118:121], v[166:169], v[182:185], v[118:121]
	v_mfma_f32_16x16x32_bf16 v[110:113], v[174:177], v[182:185], v[110:113]
	v_mfma_f32_16x16x32_bf16 v[102:105], v[166:169], v[190:193], v[102:105]
	v_mfma_f32_16x16x32_bf16 v[94:97], v[174:177], v[190:193], v[94:97]
	v_mfma_f32_16x16x32_bf16 v[86:89], v[166:169], v[198:201], v[86:89]
	v_mfma_f32_16x16x32_bf16 v[78:81], v[174:177], v[198:201], v[78:81]
	v_mfma_f32_16x16x32_bf16 v[70:73], v[166:169], v[206:209], v[70:73]
	v_mfma_f32_16x16x32_bf16 v[66:69], v[174:177], v[206:209], v[66:69]
	v_mfma_f32_16x16x32_bf16 v[118:121], v[170:173], v[186:189], v[118:121]
	v_mfma_f32_16x16x32_bf16 v[110:113], v[178:181], v[186:189], v[110:113]
	v_mfma_f32_16x16x32_bf16 v[102:105], v[170:173], v[194:197], v[102:105]
	v_mfma_f32_16x16x32_bf16 v[94:97], v[178:181], v[194:197], v[94:97]
	v_mfma_f32_16x16x32_bf16 v[86:89], v[170:173], v[202:205], v[86:89]
	v_mfma_f32_16x16x32_bf16 v[78:81], v[178:181], v[202:205], v[78:81]
	v_mfma_f32_16x16x32_bf16 v[70:73], v[170:173], v[210:213], v[70:73]
	s_barrier
	v_mfma_f32_16x16x32_bf16 v[66:69], v[178:181], v[210:213], v[66:69]
	s_setprio 0
	s_add_i32 s51, s45, s38
	v_lshl_add_u64 v[214:215], s[22:23], 0, v[130:131]
	s_mov_b32 m0, s51
	ds_read_b128 v[182:185], v149 offset:16384
	ds_read_b128 v[186:189], v149 offset:17408
	ds_read_b128 v[190:193], v149 offset:18432
	ds_read_b128 v[194:197], v149 offset:19456
	ds_read_b128 v[198:201], v149 offset:20480
	ds_read_b128 v[202:205], v149 offset:21504
	ds_read_b128 v[206:209], v149 offset:22528
	ds_read_b128 v[210:213], v149 offset:23552
	global_load_lds_dwordx4 v[214:215], off
	s_add_i32 m0, s51, 0x2000
	s_add_u32 s52, s22, 0x40000
	v_lshl_add_u64 v[216:217], s[22:23], 0, v[132:133]
	s_addc_u32 s53, s23, 0
	s_add_i32 s51, s46, s38
	global_load_lds_dwordx4 v[216:217], off
	v_lshl_add_u64 v[218:219], s[52:53], 0, v[130:131]
	s_mov_b32 m0, s51
	v_lshl_add_u64 v[220:221], s[24:25], 0, v[132:133]
	global_load_lds_dwordx4 v[218:219], off
	v_lshl_add_u64 v[218:219], s[52:53], 0, v[132:133]
	s_add_i32 m0, s51, 0x2000
	s_nop 0
	global_load_lds_dwordx4 v[218:219], off
	v_lshl_add_u64 v[218:219], s[24:25], 0, v[130:131]
	s_mov_b32 m0, s5
	s_nop 0
	global_load_lds_dwordx4 v[218:219], off
	s_mov_b32 m0, s39
	s_nop 0
	global_load_lds_dwordx4 v[220:221], off
	s_waitcnt vmcnt(8)
	s_waitcnt lgkmcnt(0)
	s_barrier
; #define PG8_STAGE(bufoff, gbase, voff) do { _Pragma("unroll") for (int _i = 0; _i < 2; ++_i) \
;         __builtin_amdgcn_global_load_lds((const unsigned*)((const char*)(gbase) + (voff)[_i]), (PG8_LAS unsigned*)(lds + (bufoff) + ldsw + _i * 8192), 16, 0, 0); } while (0)
; #define PG8_LDA(dst, b, h) do { _Pragma("unroll") for (int m = 0; m < 4; ++m) _Pragma("unroll") for (int k = 0; k < 2; ++k) dst[m][k] = *(const PG8_LAS bf16x8*)(lds + PG8_SA(b, h) + aoff + m * 2048 + k * 1024); } while (0)
; #define PG8_LDB(dst, b, h) do { _Pragma("unroll") for (int n = 0; n < 2; ++n) _Pragma("unroll") for (int k = 0; k < 2; ++k) dst[n][k] = *(const PG8_LAS bf16x8*)(lds + PG8_SB(b, h) + boff + n * 2048 + k * 1024); } while (0)
; #define PG8_MMA(ai, bj, At, Bt) do { __builtin_amdgcn_s_setprio(1); _Pragma("unroll") for (int m = 0; m < 4; ++m) _Pragma("unroll") for (int n = 0; n < 2; ++n) _Pragma("unroll") for (int k = 0; k < 2; ++k) \
;         acc[ai][bj][m][n] = __builtin_amdgcn_mfma_f32_16x16x32_bf16(Bt[n][k], At[m][k], acc[ai][bj][m][n], 0, 0, 0); __builtin_amdgcn_s_setprio(0); } while (0)
; #define PG8_WAIT_V(n) asm volatile("s_waitcnt vmcnt(" #n ")" ::: "memory")
; #define PG8_WAIT_L(n) asm volatile("s_waitcnt lgkmcnt(" #n ")" ::: "memory")
; #define PG8_BAR __builtin_amdgcn_s_barrier()
; #define PG8_SCHED __builtin_amdgcn_sched_barrier(0)
; template <class Epi, class Sched, bool ALIGN_EPI = false, bool SP2 = false>
; __device__ __forceinline__ void gemm_phase(PG8_LAS unsigned char* lds, const Gemm g, const Sched& S, const Epi& E) {
;     ...
;             PG8_WAIT_V(8); PG8_WAIT_L(0); PG8_BAR; PG8_MMA(1, 0, At, B0); PG8_MMA(1, 1, At, B1); PG8_BAR; PG8_SCHED;
;             PG8_LDB(B0, 1, 0); PG8_LDB(B1, 1, 1); PG8_SCHED; PG8_LDA(At, 1, 0); PG8_STAGE(PG8_SA(0, 1), a2 + hstep, voffA);
;             PG8_WAIT_V(8); PG8_WAIT_L(0); PG8_BAR; PG8_MMA(0, 0, At, B0); PG8_MMA(0, 1, At, B1); PG8_BAR; PG8_SCHED;
	s_setprio 1
	s_waitcnt lgkmcnt(0)
	v_mfma_f32_16x16x32_bf16 v[62:65], v[150:153], v[182:185], v[62:65]
	v_mfma_f32_16x16x32_bf16 v[58:61], v[158:161], v[182:185], v[58:61]
	v_mfma_f32_16x16x32_bf16 v[50:53], v[150:153], v[190:193], v[50:53]
	v_mfma_f32_16x16x32_bf16 v[42:45], v[158:161], v[190:193], v[42:45]
	v_mfma_f32_16x16x32_bf16 v[34:37], v[150:153], v[198:201], v[34:37]
	v_mfma_f32_16x16x32_bf16 v[26:29], v[158:161], v[198:201], v[26:29]
	v_mfma_f32_16x16x32_bf16 v[18:21], v[150:153], v[206:209], v[18:21]
	v_mfma_f32_16x16x32_bf16 v[10:13], v[158:161], v[206:209], v[10:13]
	v_mfma_f32_16x16x32_bf16 v[62:65], v[154:157], v[186:189], v[62:65]
	v_mfma_f32_16x16x32_bf16 v[58:61], v[162:165], v[186:189], v[58:61]
	v_mfma_f32_16x16x32_bf16 v[50:53], v[154:157], v[194:197], v[50:53]
	v_mfma_f32_16x16x32_bf16 v[42:45], v[162:165], v[194:197], v[42:45]
	v_mfma_f32_16x16x32_bf16 v[34:37], v[154:157], v[202:205], v[34:37]
	v_mfma_f32_16x16x32_bf16 v[26:29], v[162:165], v[202:205], v[26:29]
	v_mfma_f32_16x16x32_bf16 v[18:21], v[154:157], v[210:213], v[18:21]
	v_mfma_f32_16x16x32_bf16 v[10:13], v[162:165], v[210:213], v[10:13]
	s_setprio 0
	s_setprio 1
	v_mfma_f32_16x16x32_bf16 v[54:57], v[166:169], v[182:185], v[54:57]
	v_mfma_f32_16x16x32_bf16 v[46:49], v[174:177], v[182:185], v[46:49]
	v_mfma_f32_16x16x32_bf16 v[38:41], v[166:169], v[190:193], v[38:41]
	v_mfma_f32_16x16x32_bf16 v[30:33], v[174:177], v[190:193], v[30:33]
	v_mfma_f32_16x16x32_bf16 v[22:25], v[166:169], v[198:201], v[22:25]
	v_mfma_f32_16x16x32_bf16 v[14:17], v[174:177], v[198:201], v[14:17]
	v_mfma_f32_16x16x32_bf16 v[6:9], v[166:169], v[206:209], v[6:9]
	v_mfma_f32_16x16x32_bf16 v[2:5], v[174:177], v[206:209], v[2:5]
	v_mfma_f32_16x16x32_bf16 v[54:57], v[170:173], v[186:189], v[54:57]
	v_mfma_f32_16x16x32_bf16 v[46:49], v[178:181], v[186:189], v[46:49]
	v_mfma_f32_16x16x32_bf16 v[38:41], v[170:173], v[194:197], v[38:41]
	v_mfma_f32_16x16x32_bf16 v[30:33], v[178:181], v[194:197], v[30:33]
	v_mfma_f32_16x16x32_bf16 v[22:25], v[170:173], v[202:205], v[22:25]
	v_mfma_f32_16x16x32_bf16 v[14:17], v[178:181], v[202:205], v[14:17]
	v_mfma_f32_16x16x32_bf16 v[6:9], v[170:173], v[210:213], v[6:9]
	s_barrier
	v_mfma_f32_16x16x32_bf16 v[2:5], v[178:181], v[210:213], v[2:5]
	s_setprio 0
	s_add_i32 s51, 0, 0x18000
	s_add_i32 s52, 0, 0x1c000
	v_add_u32_e32 v162, s51, v148
	v_add_u32_e32 v178, s52, v148
	ds_read_b128 v[150:153], v162
	ds_read_b128 v[154:157], v162 offset:1024
	ds_read_b128 v[158:161], v162 offset:2048
	ds_read_b128 v[162:165], v162 offset:3072
	ds_read_b128 v[166:169], v178
	ds_read_b128 v[170:173], v178 offset:1024
	ds_read_b128 v[174:177], v178 offset:2048
	ds_read_b128 v[178:181], v178 offset:3072
	s_add_u32 s24, s24, 0x40000
	s_addc_u32 s25, s25, 0
	s_mov_b32 m0, s40
	v_lshl_add_u64 v[222:223], s[24:25], 0, v[130:131]
	ds_read_b128 v[182:185], v149 offset:32768
	ds_read_b128 v[186:189], v149 offset:33792
	ds_read_b128 v[190:193], v149 offset:34816
	ds_read_b128 v[194:197], v149 offset:35840
	ds_read_b128 v[198:201], v149 offset:36864
	ds_read_b128 v[202:205], v149 offset:37888
	ds_read_b128 v[206:209], v149 offset:38912
	ds_read_b128 v[210:213], v149 offset:39936
	global_load_lds_dwordx4 v[222:223], off
	v_lshl_add_u64 v[222:223], s[24:25], 0, v[132:133]
	s_mov_b32 m0, s41
	s_nop 0
	global_load_lds_dwordx4 v[222:223], off
	s_waitcnt vmcnt(8)
	s_waitcnt lgkmcnt(0)
	s_barrier
	s_setprio 1
	s_waitcnt lgkmcnt(0)
	v_mfma_f32_16x16x32_bf16 v[126:129], v[150:153], v[182:185], v[126:129]
	v_mfma_f32_16x16x32_bf16 v[122:125], v[158:161], v[182:185], v[122:125]
	v_mfma_f32_16x16x32_bf16 v[114:117], v[150:153], v[190:193], v[114:117]
	v_mfma_f32_16x16x32_bf16 v[106:109], v[158:161], v[190:193], v[106:109]
	v_mfma_f32_16x16x32_bf16 v[98:101], v[150:153], v[198:201], v[98:101]
	v_mfma_f32_16x16x32_bf16 v[90:93], v[158:161], v[198:201], v[90:93]
	v_mfma_f32_16x16x32_bf16 v[82:85], v[150:153], v[206:209], v[82:85]
	v_mfma_f32_16x16x32_bf16 v[74:77], v[158:161], v[206:209], v[74:77]
	v_mfma_f32_16x16x32_bf16 v[126:129], v[154:157], v[186:189], v[126:129]
	v_mfma_f32_16x16x32_bf16 v[122:125], v[162:165], v[186:189], v[122:125]
	v_mfma_f32_16x16x32_bf16 v[114:117], v[154:157], v[194:197], v[114:117]
	v_mfma_f32_16x16x32_bf16 v[106:109], v[162:165], v[194:197], v[106:109]
	v_mfma_f32_16x16x32_bf16 v[98:101], v[154:157], v[202:205], v[98:101]
	v_mfma_f32_16x16x32_bf16 v[90:93], v[162:165], v[202:205], v[90:93]
	v_mfma_f32_16x16x32_bf16 v[82:85], v[154:157], v[210:213], v[82:85]
	v_mfma_f32_16x16x32_bf16 v[74:77], v[162:165], v[210:213], v[74:77]
	s_setprio 0
	s_setprio 1
	v_mfma_f32_16x16x32_bf16 v[118:121], v[166:169], v[182:185], v[118:121]
	v_mfma_f32_16x16x32_bf16 v[110:113], v[174:177], v[182:185], v[110:113]
	v_mfma_f32_16x16x32_bf16 v[102:105], v[166:169], v[190:193], v[102:105]
	v_mfma_f32_16x16x32_bf16 v[94:97], v[174:177], v[190:193], v[94:97]
	v_mfma_f32_16x16x32_bf16 v[86:89], v[166:169], v[198:201], v[86:89]
	v_mfma_f32_16x16x32_bf16 v[78:81], v[174:177], v[198:201], v[78:81]
	v_mfma_f32_16x16x32_bf16 v[70:73], v[166:169], v[206:209], v[70:73]
	v_mfma_f32_16x16x32_bf16 v[66:69], v[174:177], v[206:209], v[66:69]
	v_mfma_f32_16x16x32_bf16 v[118:121], v[170:173], v[186:189], v[118:121]
	v_mfma_f32_16x16x32_bf16 v[110:113], v[178:181], v[186:189], v[110:113]
	v_mfma_f32_16x16x32_bf16 v[102:105], v[170:173], v[194:197], v[102:105]
	v_mfma_f32_16x16x32_bf16 v[94:97], v[178:181], v[194:197], v[94:97]
	v_mfma_f32_16x16x32_bf16 v[86:89], v[170:173], v[202:205], v[86:89]
	v_mfma_f32_16x16x32_bf16 v[78:81], v[178:181], v[202:205], v[78:81]
	v_mfma_f32_16x16x32_bf16 v[70:73], v[170:173], v[210:213], v[70:73]
	s_barrier
; #define PG8_STAGE(bufoff, gbase, voff) do { _Pragma("unroll") for (int _i = 0; _i < 2; ++_i) \
;         __builtin_amdgcn_global_load_lds((const unsigned*)((const char*)(gbase) + (voff)[_i]), (PG8_LAS unsigned*)(lds + (bufoff) + ldsw + _i * 8192), 16, 0, 0); } while (0)
; #define PG8_LDA(dst, b, h) do { _Pragma("unroll") for (int m = 0; m < 4; ++m) _Pragma("unroll") for (int k = 0; k < 2; ++k) dst[m][k] = *(const PG8_LAS bf16x8*)(lds + PG8_SA(b, h) + aoff + m * 2048 + k * 1024); } while (0)
; #define PG8_MMA(ai, bj, At, Bt) do { __builtin_amdgcn_s_setprio(1); _Pragma("unroll") for (int m = 0; m < 4; ++m) _Pragma("unroll") for (int n = 0; n < 2; ++n) _Pragma("unroll") for (int k = 0; k < 2; ++k) \
;         acc[ai][bj][m][n] = __builtin_amdgcn_mfma_f32_16x16x32_bf16(Bt[n][k], At[m][k], acc[ai][bj][m][n], 0, 0, 0); __builtin_amdgcn_s_setprio(0); } while (0)
; #define PG8_WAIT_V(n) asm volatile("s_waitcnt vmcnt(" #n ")" ::: "memory")
; #define PG8_WAIT_L(n) asm volatile("s_waitcnt lgkmcnt(" #n ")" ::: "memory")
; #define PG8_BAR __builtin_amdgcn_s_barrier()
; #define PG8_SCHED __builtin_amdgcn_sched_barrier(0)
; template <class Epi, class Sched, bool ALIGN_EPI = false, bool SP2 = false>
; __device__ __forceinline__ void gemm_phase(PG8_LAS unsigned char* lds, const Gemm g, const Sched& S, const Epi& E) {
;     ...
;             PG8_LDA(At, 1, 1); PG8_STAGE(PG8_SB(1, 0), b3, voffB); PG8_STAGE(PG8_SB(1, 1), b3 + hstep, voffB); PG8_STAGE(PG8_SA(1, 0), a3, voffA);
;             PG8_WAIT_V(8); PG8_WAIT_L(0); PG8_BAR; PG8_MMA(1, 0, At, B0); PG8_MMA(1, 1, At, B1); PG8_BAR; PG8_SCHED;
;     ...
;         if (!has_next) break;
; #pragma unroll
;         for (int a = 0; a < 2; ++a)
; #pragma unroll
;             for (int b = 0; b < 2; ++b)
; #pragma unroll
;                 for (int m = 0; m < 4; ++m)
; #pragma unroll
;                     for (int n = 0; n < 2; ++n) acc[a][b][m][n] = (f32x4){0.f, 0.f, 0.f, 0.f};
;         cur = nxt; cA = nA; cB = nB; ++ui;
	v_mfma_f32_16x16x32_bf16 v[66:69], v[178:181], v[210:213], v[66:69]
	s_setprio 0
	s_add_i32 s24, s51, s38
	v_lshl_add_u64 v[214:215], v[214:215], 0, s[10:11]
	s_mov_b32 m0, s24
	ds_read_b128 v[182:185], v149 offset:49152
	ds_read_b128 v[186:189], v149 offset:50176
	ds_read_b128 v[190:193], v149 offset:51200
	ds_read_b128 v[194:197], v149 offset:52224
	ds_read_b128 v[198:201], v149 offset:53248
	ds_read_b128 v[202:205], v149 offset:54272
	ds_read_b128 v[206:209], v149 offset:55296
	ds_read_b128 v[210:213], v149 offset:56320
	global_load_lds_dwordx4 v[214:215], off
	s_add_i32 m0, s24, 0x2000
	s_add_u32 s22, s22, 0x40080
	v_lshl_add_u64 v[214:215], v[216:217], 0, s[10:11]
	s_addc_u32 s23, s23, 0
	s_add_i32 s24, s52, s38
	global_load_lds_dwordx4 v[214:215], off
	v_lshl_add_u64 v[214:215], s[22:23], 0, v[130:131]
	s_mov_b32 m0, s24
	s_nop 0
	global_load_lds_dwordx4 v[214:215], off
	v_lshl_add_u64 v[214:215], s[22:23], 0, v[132:133]
	s_add_i32 m0, s24, 0x2000
	s_nop 0
	global_load_lds_dwordx4 v[214:215], off
	v_lshl_add_u64 v[214:215], v[218:219], 0, s[10:11]
	s_mov_b32 m0, s42
	s_nop 0
	global_load_lds_dwordx4 v[214:215], off
	v_lshl_add_u64 v[214:215], v[220:221], 0, s[10:11]
	s_mov_b32 m0, s43
	s_nop 0
	global_load_lds_dwordx4 v[214:215], off
	s_waitcnt vmcnt(8)
	s_waitcnt lgkmcnt(0)
	s_barrier
	s_setprio 1
	s_waitcnt lgkmcnt(0)
	v_mfma_f32_16x16x32_bf16 v[62:65], v[150:153], v[182:185], v[62:65]
	v_mfma_f32_16x16x32_bf16 v[58:61], v[158:161], v[182:185], v[58:61]
	v_mfma_f32_16x16x32_bf16 v[50:53], v[150:153], v[190:193], v[50:53]
	v_mfma_f32_16x16x32_bf16 v[42:45], v[158:161], v[190:193], v[42:45]
	v_mfma_f32_16x16x32_bf16 v[34:37], v[150:153], v[198:201], v[34:37]
	v_mfma_f32_16x16x32_bf16 v[26:29], v[158:161], v[198:201], v[26:29]
	v_mfma_f32_16x16x32_bf16 v[18:21], v[150:153], v[206:209], v[18:21]
	v_mfma_f32_16x16x32_bf16 v[10:13], v[158:161], v[206:209], v[10:13]
	v_mfma_f32_16x16x32_bf16 v[62:65], v[154:157], v[186:189], v[62:65]
	v_mfma_f32_16x16x32_bf16 v[58:61], v[162:165], v[186:189], v[58:61]
	v_mfma_f32_16x16x32_bf16 v[50:53], v[154:157], v[194:197], v[50:53]
	v_mfma_f32_16x16x32_bf16 v[42:45], v[162:165], v[194:197], v[42:45]
	v_mfma_f32_16x16x32_bf16 v[34:37], v[154:157], v[202:205], v[34:37]
	v_mfma_f32_16x16x32_bf16 v[26:29], v[162:165], v[202:205], v[26:29]
	v_mfma_f32_16x16x32_bf16 v[18:21], v[154:157], v[210:213], v[18:21]
	v_mfma_f32_16x16x32_bf16 v[10:13], v[162:165], v[210:213], v[10:13]
	s_setprio 0
	s_setprio 1
	v_mfma_f32_16x16x32_bf16 v[54:57], v[166:169], v[182:185], v[54:57]
	v_mfma_f32_16x16x32_bf16 v[46:49], v[174:177], v[182:185], v[46:49]
	v_mfma_f32_16x16x32_bf16 v[38:41], v[166:169], v[190:193], v[38:41]
	v_mfma_f32_16x16x32_bf16 v[30:33], v[174:177], v[190:193], v[30:33]
	v_mfma_f32_16x16x32_bf16 v[22:25], v[166:169], v[198:201], v[22:25]
	v_mfma_f32_16x16x32_bf16 v[14:17], v[174:177], v[198:201], v[14:17]
	v_mfma_f32_16x16x32_bf16 v[6:9], v[166:169], v[206:209], v[6:9]
	v_mfma_f32_16x16x32_bf16 v[2:5], v[174:177], v[206:209], v[2:5]
	v_mfma_f32_16x16x32_bf16 v[54:57], v[170:173], v[186:189], v[54:57]
	v_mfma_f32_16x16x32_bf16 v[46:49], v[178:181], v[186:189], v[46:49]
	v_mfma_f32_16x16x32_bf16 v[38:41], v[170:173], v[194:197], v[38:41]
	v_mfma_f32_16x16x32_bf16 v[30:33], v[178:181], v[194:197], v[30:33]
	v_mfma_f32_16x16x32_bf16 v[22:25], v[170:173], v[202:205], v[22:25]
	v_mfma_f32_16x16x32_bf16 v[14:17], v[178:181], v[202:205], v[14:17]
	v_mfma_f32_16x16x32_bf16 v[6:9], v[170:173], v[210:213], v[6:9]
	s_barrier
	v_mfma_f32_16x16x32_bf16 v[2:5], v[178:181], v[210:213], v[2:5]
	s_setprio 0
	s_add_i32 s50, s50, 2
	s_add_u32 s20, s20, 0x100
	s_addc_u32 s21, s21, 0
	s_cmp_gt_u32 s50, 13
	s_cbranch_scc0 .LBB0_968
	s_add_u32 s20, s48, 0xffffff00
	s_addc_u32 s21, s49, -1
	s_andn2_b64 vcc, exec, s[2:3]
	s_cbranch_vccnz .LBB0_959
	v_mov_b32_e32 v2, 0
	s_mov_b32 s6, s12
	s_mov_b32 s4, s14
	s_mov_b64 s[8:9], s[18:19]
	s_mov_b32 s44, s47
	v_mov_b32_e32 v3, v2
	v_mov_b32_e32 v4, v2
	v_mov_b32_e32 v5, v2
	v_mov_b32_e32 v6, v2
	v_mov_b32_e32 v7, v2
	v_mov_b32_e32 v8, v2
	v_mov_b32_e32 v9, v2
	v_mov_b32_e32 v14, v2
	v_mov_b32_e32 v15, v2
	v_mov_b32_e32 v16, v2
	v_mov_b32_e32 v17, v2
	v_mov_b32_e32 v22, v2
	v_mov_b32_e32 v23, v2
	v_mov_b32_e32 v24, v2
	v_mov_b32_e32 v25, v2
	v_mov_b32_e32 v30, v2
	v_mov_b32_e32 v31, v2
	v_mov_b32_e32 v32, v2
	v_mov_b32_e32 v33, v2
	v_mov_b32_e32 v38, v2
	v_mov_b32_e32 v39, v2
	v_mov_b32_e32 v40, v2
	v_mov_b32_e32 v41, v2
	v_mov_b32_e32 v46, v2
	v_mov_b32_e32 v47, v2
	v_mov_b32_e32 v48, v2
	v_mov_b32_e32 v49, v2
	v_mov_b32_e32 v54, v2
	v_mov_b32_e32 v55, v2
	v_mov_b32_e32 v56, v2
	v_mov_b32_e32 v57, v2
	v_mov_b32_e32 v10, v2
	v_mov_b32_e32 v11, v2
	v_mov_b32_e32 v12, v2
	v_mov_b32_e32 v13, v2
	v_mov_b32_e32 v18, v2
	v_mov_b32_e32 v19, v2
	v_mov_b32_e32 v20, v2
	v_mov_b32_e32 v21, v2
	v_mov_b32_e32 v26, v2
	v_mov_b32_e32 v27, v2
	v_mov_b32_e32 v28, v2
	v_mov_b32_e32 v29, v2
	v_mov_b32_e32 v34, v2
	v_mov_b32_e32 v35, v2
	v_mov_b32_e32 v36, v2
	v_mov_b32_e32 v37, v2
	v_mov_b32_e32 v42, v2
	v_mov_b32_e32 v43, v2
	v_mov_b32_e32 v44, v2
	v_mov_b32_e32 v45, v2
	v_mov_b32_e32 v50, v2
	v_mov_b32_e32 v51, v2
	v_mov_b32_e32 v52, v2
	v_mov_b32_e32 v53, v2
	v_mov_b32_e32 v58, v2
	v_mov_b32_e32 v59, v2
	v_mov_b32_e32 v60, v2
	v_mov_b32_e32 v61, v2
	v_mov_b32_e32 v62, v2
	v_mov_b32_e32 v63, v2
	v_mov_b32_e32 v64, v2
	v_mov_b32_e32 v65, v2
	v_mov_b32_e32 v66, v2
	v_mov_b32_e32 v67, v2
	v_mov_b32_e32 v68, v2
	v_mov_b32_e32 v69, v2
	v_mov_b32_e32 v70, v2
	v_mov_b32_e32 v71, v2
	v_mov_b32_e32 v72, v2
	v_mov_b32_e32 v73, v2
	v_mov_b32_e32 v78, v2
	v_mov_b32_e32 v79, v2
	v_mov_b32_e32 v80, v2
	v_mov_b32_e32 v81, v2
	v_mov_b32_e32 v86, v2
	v_mov_b32_e32 v87, v2
	v_mov_b32_e32 v88, v2
	v_mov_b32_e32 v89, v2
	v_mov_b32_e32 v94, v2
	v_mov_b32_e32 v95, v2
	v_mov_b32_e32 v96, v2
	v_mov_b32_e32 v97, v2
	v_mov_b32_e32 v102, v2
	v_mov_b32_e32 v103, v2
	v_mov_b32_e32 v104, v2
	v_mov_b32_e32 v105, v2
	v_mov_b32_e32 v110, v2
	v_mov_b32_e32 v111, v2
	v_mov_b32_e32 v112, v2
	v_mov_b32_e32 v113, v2
	v_mov_b32_e32 v118, v2
	v_mov_b32_e32 v119, v2
	v_mov_b32_e32 v120, v2
	v_mov_b32_e32 v121, v2
	v_mov_b32_e32 v74, v2
	v_mov_b32_e32 v75, v2
	v_mov_b32_e32 v76, v2
	v_mov_b32_e32 v77, v2
	v_mov_b32_e32 v82, v2
	v_mov_b32_e32 v83, v2
	v_mov_b32_e32 v84, v2
	v_mov_b32_e32 v85, v2
	v_mov_b32_e32 v90, v2
	v_mov_b32_e32 v91, v2
	v_mov_b32_e32 v92, v2
	v_mov_b32_e32 v93, v2
	v_mov_b32_e32 v98, v2
	v_mov_b32_e32 v99, v2
	v_mov_b32_e32 v100, v2
	v_mov_b32_e32 v101, v2
	v_mov_b32_e32 v106, v2
	v_mov_b32_e32 v107, v2
	v_mov_b32_e32 v108, v2
	v_mov_b32_e32 v109, v2
	v_mov_b32_e32 v114, v2
	v_mov_b32_e32 v115, v2
	v_mov_b32_e32 v116, v2
	v_mov_b32_e32 v117, v2
	v_mov_b32_e32 v122, v2
	v_mov_b32_e32 v123, v2
	v_mov_b32_e32 v124, v2
	v_mov_b32_e32 v125, v2
	v_mov_b32_e32 v126, v2
	v_mov_b32_e32 v127, v2
	v_mov_b32_e32 v128, v2
	v_mov_b32_e32 v129, v2
	s_andn2_b64 vcc, exec, s[0:1]
	s_cbranch_vccnz .LBB0_960
